# first K-loop iteration of each unit peeled with srcC=0 on first-touch MFMAs; 128 accumulator-zeroing v_movs per unit removed
# speedup vs baseline: 1.0295x; 1.0120x over previous
;     __device__ __forceinline__ bool next(int i, Unit& u) const { if (i >= n) return false; int o = own; asm volatile("" : "+s"(o)); u.pm = swap ? i : o; u.pn = swap ? o : i; u.idx = i; return true; }
; #define PG8_STAGE(bufoff, gbase, voff) do { _Pragma("unroll") for (int _i = 0; _i < 2; ++_i) \
;         __builtin_amdgcn_global_load_lds((const unsigned*)((const char*)(gbase) + (voff)[_i]), (PG8_LAS unsigned*)(lds + (bufoff) + ldsw + _i * 8192), 16, 0, 0); } while (0)
; template <class Epi, class Sched, bool ALIGN_EPI = false, bool SP2 = false>
; __device__ __forceinline__ void gemm_phase(PG8_LAS unsigned char* lds, const Gemm g, const Sched& S, const Epi& E, int tid_in) {
;     ...
;         const bool has_next = S.next(ui + 1, nxt);
;         const char* nA = has_next ? (const char*)g.A + (size_t)nxt.pm * tstep : cA; const char* nB = has_next ? (const char*)g.Bt + (size_t)nxt.pn * tstep : cB;
;         for (int t = 0; t < nt; t += 2) {
;             const bool last = (t == nt - 2);
;             const char* a1 = cA + (size_t)(t + 1) * kstep;
;             const char* a2 = last ? nA : cA + (size_t)(t + 2) * kstep; const char* b2 = last ? nB : cB + (size_t)(t + 2) * kstep;
;             const char* a3 = a2 + kstep; const char* b3 = b2 + kstep;
;             if (last && has_next) S.a_ready(nxt);
;             if constexpr (SP2) {
;             PG8_LDB(B0, 0, 0); PG8_LDB(B1, 0, 1); PG8_SCHED; PG8_LDA(At, 0, 0); PG8_STAGE(PG8_SA(1, 1), a1 + hstep, voffA);
;             PG8_WAIT_V(8); PG8_WAIT_L(0); PG8_BAR; PG8_MMA(0, 0, At, B0); PG8_MMA(0, 1, At, B1); PG8_BAR; PG8_SCHED;
;             PG8_LDA(At, 0, 1); PG8_STAGE(PG8_SB(0, 0), b2, voffB); PG8_STAGE(PG8_SB(0, 1), b2 + hstep, voffB); PG8_STAGE(PG8_SA(0, 0), a2, voffA);
;             PG8_WAIT_V(8); PG8_WAIT_L(0); PG8_BAR; PG8_MMA(1, 0, At, B0); PG8_MMA(1, 1, At, B1); PG8_BAR; PG8_SCHED;
;             PG8_LDB(B0, 1, 0); PG8_LDB(B1, 1, 1); PG8_SCHED; PG8_LDA(At, 1, 0); PG8_STAGE(PG8_SA(0, 1), a2 + hstep, voffA);
;             PG8_WAIT_V(8); PG8_WAIT_L(0); PG8_BAR; PG8_MMA(0, 0, At, B0); PG8_MMA(0, 1, At, B1); PG8_BAR; PG8_SCHED;
;             PG8_LDA(At, 1, 1); PG8_STAGE(PG8_SB(1, 0), b3, voffB); PG8_STAGE(PG8_SB(1, 1), b3 + hstep, voffB); PG8_STAGE(PG8_SA(1, 0), a3, voffA);
;             PG8_WAIT_V(8); PG8_WAIT_L(0); PG8_BAR; PG8_MMA(1, 0, At, B0); PG8_MMA(1, 1, At, B1); PG8_BAR; PG8_SCHED;
.LBB0_190:
	s_ashr_i32 s41, s40, 31
	s_lshl_b64 s[46:47], s[40:41], 19
	s_add_u32 s46, s59, s46
	s_addc_u32 s47, s60, s47
	s_and_b64 s[48:49], s[44:45], exec
	s_cselect_b32 s41, s47, s51
	s_cselect_b32 s79, s46, s50
	s_ashr_i32 s43, s42, 31
	s_lshl_b64 s[48:49], s[42:43], 19
	s_add_u32 s48, s33, s48
	s_addc_u32 s49, s56, s49
	s_and_b64 s[54:55], s[44:45], exec
	s_cselect_b32 s43, s49, s53
	s_cselect_b32 s80, s48, s52
	s_add_u32 s50, s50, 0x40080
	s_addc_u32 s51, s51, 0
	s_add_u32 s81, s52, 0x100
	s_addc_u32 s82, s53, 0
	s_mov_b32 s83, -2
	s_add_u32 s52, s50, 0xfffc0080
	s_addc_u32 s53, s51, -1
	s_add_i32 s84, 0, 0x10000
	s_cmp_eq_u32 s83, 12
	s_cselect_b32 s55, s41, s53
	s_cselect_b32 s54, s79, s52
	v_add_u32_e32 v149, s84, v147
	s_cselect_b32 s53, s43, s82
	s_cselect_b32 s52, s80, s81
	s_add_i32 s86, 0, 0x14000
	ds_read_b128 v[142:145], v149
	ds_read_b128 v[150:153], v149 offset:1024
	ds_read_b128 v[154:157], v149 offset:2048
	ds_read_b128 v[158:161], v149 offset:3072
	v_add_u32_e32 v149, s86, v147
	ds_read_b128 v[162:165], v149
	ds_read_b128 v[166:169], v149 offset:1024
	ds_read_b128 v[170:173], v149 offset:2048
	ds_read_b128 v[174:177], v149 offset:3072
	v_lshl_add_u64 v[220:221], s[50:51], 0, v[138:139]
	s_add_i32 m0, s61, 0xc000
	ds_read_b128 v[178:181], v148
	ds_read_b128 v[182:185], v148 offset:1024
	ds_read_b128 v[196:199], v148 offset:2048
	ds_read_b128 v[200:203], v148 offset:3072
	ds_read_b128 v[204:207], v148 offset:4096
	ds_read_b128 v[208:211], v148 offset:5120
	ds_read_b128 v[212:215], v148 offset:6144
	ds_read_b128 v[216:219], v148 offset:7168
	global_load_lds_dwordx4 v[220:221], off
	v_lshl_add_u64 v[220:221], s[50:51], 0, v[140:141]
	s_add_i32 m0, s61, 0xe000
	s_nop 0
	global_load_lds_dwordx4 v[220:221], off
	s_waitcnt vmcnt(8)
	s_waitcnt lgkmcnt(0)
	s_barrier
	s_setprio 1
	s_waitcnt lgkmcnt(0)
	v_mfma_f32_16x16x32_bf16 v[126:129], v[142:145], v[178:181], 0
	v_mfma_f32_16x16x32_bf16 v[122:125], v[154:157], v[178:181], 0
	v_mfma_f32_16x16x32_bf16 v[110:113], v[142:145], v[196:199], 0
	v_mfma_f32_16x16x32_bf16 v[106:109], v[154:157], v[196:199], 0
	v_mfma_f32_16x16x32_bf16 v[94:97], v[142:145], v[204:207], 0
	v_mfma_f32_16x16x32_bf16 v[90:93], v[154:157], v[204:207], 0
	v_mfma_f32_16x16x32_bf16 v[78:81], v[142:145], v[212:215], 0
	v_mfma_f32_16x16x32_bf16 v[74:77], v[154:157], v[212:215], 0
	v_mfma_f32_16x16x32_bf16 v[126:129], v[150:153], v[182:185], v[126:129]
	v_mfma_f32_16x16x32_bf16 v[122:125], v[158:161], v[182:185], v[122:125]
	v_mfma_f32_16x16x32_bf16 v[110:113], v[150:153], v[200:203], v[110:113]
	v_mfma_f32_16x16x32_bf16 v[106:109], v[158:161], v[200:203], v[106:109]
	v_mfma_f32_16x16x32_bf16 v[94:97], v[150:153], v[208:211], v[94:97]
	v_mfma_f32_16x16x32_bf16 v[90:93], v[158:161], v[208:211], v[90:93]
	v_mfma_f32_16x16x32_bf16 v[78:81], v[150:153], v[216:219], v[78:81]
	v_mfma_f32_16x16x32_bf16 v[74:77], v[158:161], v[216:219], v[74:77]
	s_setprio 0
	s_setprio 1
	v_mfma_f32_16x16x32_bf16 v[118:121], v[162:165], v[178:181], 0
	v_mfma_f32_16x16x32_bf16 v[114:117], v[170:173], v[178:181], 0
	v_mfma_f32_16x16x32_bf16 v[102:105], v[162:165], v[196:199], 0
	v_mfma_f32_16x16x32_bf16 v[98:101], v[170:173], v[196:199], 0
	v_mfma_f32_16x16x32_bf16 v[86:89], v[162:165], v[204:207], 0
	v_mfma_f32_16x16x32_bf16 v[82:85], v[170:173], v[204:207], 0
	v_mfma_f32_16x16x32_bf16 v[70:73], v[162:165], v[212:215], 0
	v_mfma_f32_16x16x32_bf16 v[66:69], v[170:173], v[212:215], 0
	v_mfma_f32_16x16x32_bf16 v[118:121], v[166:169], v[182:185], v[118:121]
	v_mfma_f32_16x16x32_bf16 v[114:117], v[174:177], v[182:185], v[114:117]
	v_mfma_f32_16x16x32_bf16 v[102:105], v[166:169], v[200:203], v[102:105]
	v_mfma_f32_16x16x32_bf16 v[98:101], v[174:177], v[200:203], v[98:101]
	v_mfma_f32_16x16x32_bf16 v[86:89], v[166:169], v[208:211], v[86:89]
	v_mfma_f32_16x16x32_bf16 v[82:85], v[174:177], v[208:211], v[82:85]
	v_mfma_f32_16x16x32_bf16 v[70:73], v[166:169], v[216:219], v[70:73]
	v_mfma_f32_16x16x32_bf16 v[66:69], v[174:177], v[216:219], v[66:69]
	s_setprio 0
	s_barrier
	s_add_i32 s84, s84, s57
	v_lshl_add_u64 v[220:221], s[52:53], 0, v[0:1]
	s_mov_b32 m0, s84
	ds_read_b128 v[178:181], v148 offset:16384
	ds_read_b128 v[182:185], v148 offset:17408
	ds_read_b128 v[196:199], v148 offset:18432
	ds_read_b128 v[200:203], v148 offset:19456
	ds_read_b128 v[204:207], v148 offset:20480
	ds_read_b128 v[208:211], v148 offset:21504
	ds_read_b128 v[212:215], v148 offset:22528
	ds_read_b128 v[216:219], v148 offset:23552
	global_load_lds_dwordx4 v[220:221], off
	s_add_i32 m0, s84, 0x2000
	s_add_u32 s84, s52, 0x40000
	v_lshl_add_u64 v[222:223], s[52:53], 0, v[132:133]
	s_addc_u32 s85, s53, 0
	s_add_i32 s86, s86, s57
	global_load_lds_dwordx4 v[222:223], off
	v_lshl_add_u64 v[224:225], s[84:85], 0, v[0:1]
	s_mov_b32 m0, s86
	v_lshl_add_u64 v[226:227], s[54:55], 0, v[134:135]
	global_load_lds_dwordx4 v[224:225], off
	v_lshl_add_u64 v[224:225], s[84:85], 0, v[132:133]
	s_add_i32 m0, s86, 0x2000
	s_nop 0
	global_load_lds_dwordx4 v[224:225], off
	v_lshl_add_u64 v[224:225], s[54:55], 0, v[136:137]
	s_mov_b32 m0, s61
	s_nop 0
	global_load_lds_dwordx4 v[224:225], off
	s_mov_b32 m0, s62
	s_nop 0
	global_load_lds_dwordx4 v[226:227], off
	s_waitcnt vmcnt(8)
	s_waitcnt lgkmcnt(0)
	s_barrier
; #define PG8_STAGE(bufoff, gbase, voff) do { _Pragma("unroll") for (int _i = 0; _i < 2; ++_i) \
;         __builtin_amdgcn_global_load_lds((const unsigned*)((const char*)(gbase) + (voff)[_i]), (PG8_LAS unsigned*)(lds + (bufoff) + ldsw + _i * 8192), 16, 0, 0); } while (0)
; #define PG8_LDA(dst, b, h) do { _Pragma("unroll") for (int m = 0; m < 4; ++m) _Pragma("unroll") for (int k = 0; k < 2; ++k) dst[m][k] = *(const PG8_LAS bf16x8*)(lds + PG8_SA(b, h) + aoff + m * 2048 + k * 1024); } while (0)
; #define PG8_LDB(dst, b, h) do { _Pragma("unroll") for (int n = 0; n < 2; ++n) _Pragma("unroll") for (int k = 0; k < 2; ++k) dst[n][k] = *(const PG8_LAS bf16x8*)(lds + PG8_SB(b, h) + boff + n * 2048 + k * 1024); } while (0)
; #define PG8_MMA(ai, bj, At, Bt) do { __builtin_amdgcn_s_setprio(1); _Pragma("unroll") for (int k = 0; k < 2; ++k) _Pragma("unroll") for (int m = 0; m < 4; ++m) _Pragma("unroll") for (int n = 0; n < 2; ++n) \
;         acc[ai][bj][m][n] = __builtin_amdgcn_mfma_f32_16x16x32_bf16(Bt[n][k], At[m][k], acc[ai][bj][m][n], 0, 0, 0); __builtin_amdgcn_s_setprio(0); } while (0)
; #define PG8_WAIT_V(n) asm volatile("s_waitcnt vmcnt(" #n ")" ::: "memory")
; #define PG8_WAIT_L(n) asm volatile("s_waitcnt lgkmcnt(" #n ")" ::: "memory")
; template <class Epi, class Sched, bool ALIGN_EPI = false, bool SP2 = false>
; __device__ __forceinline__ void gemm_phase(PG8_LAS unsigned char* lds, const Gemm g, const Sched& S, const Epi& E, int tid_in) {
;     ...
;             PG8_WAIT_V(8); PG8_WAIT_L(0); PG8_BAR; PG8_MMA(0, 0, At, B0); PG8_MMA(0, 1, At, B1); PG8_BAR; PG8_SCHED;
;             PG8_LDA(At, 0, 1); PG8_STAGE(PG8_SB(0, 0), b2, voffB); PG8_STAGE(PG8_SB(0, 1), b2 + hstep, voffB); PG8_STAGE(PG8_SA(0, 0), a2, voffA);
;             PG8_WAIT_V(8); PG8_WAIT_L(0); PG8_BAR; PG8_MMA(1, 0, At, B0); PG8_MMA(1, 1, At, B1); PG8_BAR; PG8_SCHED;
;             PG8_LDB(B0, 1, 0); PG8_LDB(B1, 1, 1); PG8_SCHED; PG8_LDA(At, 1, 0); PG8_STAGE(PG8_SA(0, 1), a2 + hstep, voffA);
;             PG8_WAIT_V(8); PG8_WAIT_L(0); PG8_BAR; PG8_MMA(0, 0, At, B0); PG8_MMA(0, 1, At, B1); PG8_BAR; PG8_SCHED;
;             PG8_LDA(At, 1, 1); PG8_STAGE(PG8_SB(1, 0), b3, voffB); PG8_STAGE(PG8_SB(1, 1), b3 + hstep, voffB); PG8_STAGE(PG8_SA(1, 0), a3, voffA);
;             PG8_WAIT_V(8); PG8_WAIT_L(0); PG8_BAR; PG8_MMA(1, 0, At, B0); PG8_MMA(1, 1, At, B1); PG8_BAR; PG8_SCHED;
	s_setprio 1
	s_waitcnt lgkmcnt(0)
	v_mfma_f32_16x16x32_bf16 v[62:65], v[142:145], v[178:181], 0
	v_mfma_f32_16x16x32_bf16 v[58:61], v[154:157], v[178:181], 0
	v_mfma_f32_16x16x32_bf16 v[46:49], v[142:145], v[196:199], 0
	v_mfma_f32_16x16x32_bf16 v[42:45], v[154:157], v[196:199], 0
	v_mfma_f32_16x16x32_bf16 v[30:33], v[142:145], v[204:207], 0
	v_mfma_f32_16x16x32_bf16 v[26:29], v[154:157], v[204:207], 0
	v_mfma_f32_16x16x32_bf16 v[14:17], v[142:145], v[212:215], 0
	v_mfma_f32_16x16x32_bf16 v[10:13], v[154:157], v[212:215], 0
	v_mfma_f32_16x16x32_bf16 v[62:65], v[150:153], v[182:185], v[62:65]
	v_mfma_f32_16x16x32_bf16 v[58:61], v[158:161], v[182:185], v[58:61]
	v_mfma_f32_16x16x32_bf16 v[46:49], v[150:153], v[200:203], v[46:49]
	v_mfma_f32_16x16x32_bf16 v[42:45], v[158:161], v[200:203], v[42:45]
	v_mfma_f32_16x16x32_bf16 v[30:33], v[150:153], v[208:211], v[30:33]
	v_mfma_f32_16x16x32_bf16 v[26:29], v[158:161], v[208:211], v[26:29]
	v_mfma_f32_16x16x32_bf16 v[14:17], v[150:153], v[216:219], v[14:17]
	v_mfma_f32_16x16x32_bf16 v[10:13], v[158:161], v[216:219], v[10:13]
	s_setprio 0
	s_setprio 1
	v_mfma_f32_16x16x32_bf16 v[54:57], v[162:165], v[178:181], 0
	v_mfma_f32_16x16x32_bf16 v[50:53], v[170:173], v[178:181], 0
	v_mfma_f32_16x16x32_bf16 v[38:41], v[162:165], v[196:199], 0
	v_mfma_f32_16x16x32_bf16 v[34:37], v[170:173], v[196:199], 0
	v_mfma_f32_16x16x32_bf16 v[22:25], v[162:165], v[204:207], 0
	v_mfma_f32_16x16x32_bf16 v[18:21], v[170:173], v[204:207], 0
	v_mfma_f32_16x16x32_bf16 v[6:9], v[162:165], v[212:215], 0
	v_mfma_f32_16x16x32_bf16 v[2:5], v[170:173], v[212:215], 0
	v_mfma_f32_16x16x32_bf16 v[54:57], v[166:169], v[182:185], v[54:57]
	v_mfma_f32_16x16x32_bf16 v[50:53], v[174:177], v[182:185], v[50:53]
	v_mfma_f32_16x16x32_bf16 v[38:41], v[166:169], v[200:203], v[38:41]
	v_mfma_f32_16x16x32_bf16 v[34:37], v[174:177], v[200:203], v[34:37]
	v_mfma_f32_16x16x32_bf16 v[22:25], v[166:169], v[208:211], v[22:25]
	v_mfma_f32_16x16x32_bf16 v[18:21], v[174:177], v[208:211], v[18:21]
	v_mfma_f32_16x16x32_bf16 v[6:9], v[166:169], v[216:219], v[6:9]
	v_mfma_f32_16x16x32_bf16 v[2:5], v[174:177], v[216:219], v[2:5]
	s_setprio 0
	s_barrier
	s_add_i32 s84, 0, 0x18000
	v_add_u32_e32 v149, s84, v147
	s_add_i32 s85, 0, 0x1c000
	ds_read_b128 v[142:145], v149
	ds_read_b128 v[150:153], v149 offset:1024
	ds_read_b128 v[154:157], v149 offset:2048
	ds_read_b128 v[158:161], v149 offset:3072
	v_add_u32_e32 v149, s85, v147
	ds_read_b128 v[162:165], v149
	ds_read_b128 v[166:169], v149 offset:1024
	ds_read_b128 v[170:173], v149 offset:2048
	ds_read_b128 v[174:177], v149 offset:3072
	s_add_u32 s54, s54, 0x40000
	s_addc_u32 s55, s55, 0
	s_mov_b32 m0, s63
	v_lshl_add_u64 v[228:229], s[54:55], 0, v[136:137]
	ds_read_b128 v[178:181], v148 offset:32768
	ds_read_b128 v[182:185], v148 offset:33792
	ds_read_b128 v[196:199], v148 offset:34816
	ds_read_b128 v[200:203], v148 offset:35840
	ds_read_b128 v[204:207], v148 offset:36864
	ds_read_b128 v[208:211], v148 offset:37888
	ds_read_b128 v[212:215], v148 offset:38912
	ds_read_b128 v[216:219], v148 offset:39936
	global_load_lds_dwordx4 v[228:229], off
	v_lshl_add_u64 v[228:229], s[54:55], 0, v[134:135]
	s_mov_b32 m0, s64
	s_nop 0
	global_load_lds_dwordx4 v[228:229], off
	s_waitcnt vmcnt(8)
	s_waitcnt lgkmcnt(0)
	s_barrier
	s_setprio 1
	s_waitcnt lgkmcnt(0)
	v_mfma_f32_16x16x32_bf16 v[126:129], v[142:145], v[178:181], v[126:129]
	v_mfma_f32_16x16x32_bf16 v[122:125], v[154:157], v[178:181], v[122:125]
	v_mfma_f32_16x16x32_bf16 v[110:113], v[142:145], v[196:199], v[110:113]
	v_mfma_f32_16x16x32_bf16 v[106:109], v[154:157], v[196:199], v[106:109]
	v_mfma_f32_16x16x32_bf16 v[94:97], v[142:145], v[204:207], v[94:97]
	v_mfma_f32_16x16x32_bf16 v[90:93], v[154:157], v[204:207], v[90:93]
	v_mfma_f32_16x16x32_bf16 v[78:81], v[142:145], v[212:215], v[78:81]
	v_mfma_f32_16x16x32_bf16 v[74:77], v[154:157], v[212:215], v[74:77]
	v_mfma_f32_16x16x32_bf16 v[126:129], v[150:153], v[182:185], v[126:129]
	v_mfma_f32_16x16x32_bf16 v[122:125], v[158:161], v[182:185], v[122:125]
	v_mfma_f32_16x16x32_bf16 v[110:113], v[150:153], v[200:203], v[110:113]
	v_mfma_f32_16x16x32_bf16 v[106:109], v[158:161], v[200:203], v[106:109]
	v_mfma_f32_16x16x32_bf16 v[94:97], v[150:153], v[208:211], v[94:97]
	v_mfma_f32_16x16x32_bf16 v[90:93], v[158:161], v[208:211], v[90:93]
	v_mfma_f32_16x16x32_bf16 v[78:81], v[150:153], v[216:219], v[78:81]
	v_mfma_f32_16x16x32_bf16 v[74:77], v[158:161], v[216:219], v[74:77]
	s_setprio 0
	s_setprio 1
	v_mfma_f32_16x16x32_bf16 v[118:121], v[162:165], v[178:181], v[118:121]
	v_mfma_f32_16x16x32_bf16 v[114:117], v[170:173], v[178:181], v[114:117]
	v_mfma_f32_16x16x32_bf16 v[102:105], v[162:165], v[196:199], v[102:105]
	v_mfma_f32_16x16x32_bf16 v[98:101], v[170:173], v[196:199], v[98:101]
	v_mfma_f32_16x16x32_bf16 v[86:89], v[162:165], v[204:207], v[86:89]
	v_mfma_f32_16x16x32_bf16 v[82:85], v[170:173], v[204:207], v[82:85]
	v_mfma_f32_16x16x32_bf16 v[70:73], v[162:165], v[212:215], v[70:73]
	v_mfma_f32_16x16x32_bf16 v[66:69], v[170:173], v[212:215], v[66:69]
	v_mfma_f32_16x16x32_bf16 v[118:121], v[166:169], v[182:185], v[118:121]
	v_mfma_f32_16x16x32_bf16 v[114:117], v[174:177], v[182:185], v[114:117]
	v_mfma_f32_16x16x32_bf16 v[102:105], v[166:169], v[200:203], v[102:105]
	v_mfma_f32_16x16x32_bf16 v[98:101], v[174:177], v[200:203], v[98:101]
	v_mfma_f32_16x16x32_bf16 v[86:89], v[166:169], v[208:211], v[86:89]
	v_mfma_f32_16x16x32_bf16 v[82:85], v[174:177], v[208:211], v[82:85]
	v_mfma_f32_16x16x32_bf16 v[70:73], v[166:169], v[216:219], v[70:73]
	v_mfma_f32_16x16x32_bf16 v[66:69], v[174:177], v[216:219], v[66:69]
	s_setprio 0
	s_barrier
; #define PG8_STAGE(bufoff, gbase, voff) do { _Pragma("unroll") for (int _i = 0; _i < 2; ++_i) \
;         __builtin_amdgcn_global_load_lds((const unsigned*)((const char*)(gbase) + (voff)[_i]), (PG8_LAS unsigned*)(lds + (bufoff) + ldsw + _i * 8192), 16, 0, 0); } while (0)
; #define PG8_LDA(dst, b, h) do { _Pragma("unroll") for (int m = 0; m < 4; ++m) _Pragma("unroll") for (int k = 0; k < 2; ++k) dst[m][k] = *(const PG8_LAS bf16x8*)(lds + PG8_SA(b, h) + aoff + m * 2048 + k * 1024); } while (0)
; #define PG8_MMA(ai, bj, At, Bt) do { __builtin_amdgcn_s_setprio(1); _Pragma("unroll") for (int k = 0; k < 2; ++k) _Pragma("unroll") for (int m = 0; m < 4; ++m) _Pragma("unroll") for (int n = 0; n < 2; ++n) \
;         acc[ai][bj][m][n] = __builtin_amdgcn_mfma_f32_16x16x32_bf16(Bt[n][k], At[m][k], acc[ai][bj][m][n], 0, 0, 0); __builtin_amdgcn_s_setprio(0); } while (0)
; #define PG8_WAIT_V(n) asm volatile("s_waitcnt vmcnt(" #n ")" ::: "memory")
; #define PG8_WAIT_L(n) asm volatile("s_waitcnt lgkmcnt(" #n ")" ::: "memory")
; #define PG8_BAR __builtin_amdgcn_s_barrier()
; #define PG8_SCHED __builtin_amdgcn_sched_barrier(0)
; template <class Epi, class Sched, bool ALIGN_EPI = false, bool SP2 = false>
; __device__ __forceinline__ void gemm_phase(PG8_LAS unsigned char* lds, const Gemm g, const Sched& S, const Epi& E, int tid_in) {
;     ...
;         for (int t = 0; t < nt; t += 2) {
;     ...
;             PG8_LDA(At, 1, 1); PG8_STAGE(PG8_SB(1, 0), b3, voffB); PG8_STAGE(PG8_SB(1, 1), b3 + hstep, voffB); PG8_STAGE(PG8_SA(1, 0), a3, voffA);
;             PG8_WAIT_V(8); PG8_WAIT_L(0); PG8_BAR; PG8_MMA(1, 0, At, B0); PG8_MMA(1, 1, At, B1); PG8_BAR; PG8_SCHED;
	s_add_i32 s54, s84, s57
	v_lshl_add_u64 v[220:221], v[220:221], 0, s[26:27]
	s_mov_b32 m0, s54
	ds_read_b128 v[178:181], v148 offset:49152
	ds_read_b128 v[182:185], v148 offset:50176
	ds_read_b128 v[196:199], v148 offset:51200
	ds_read_b128 v[200:203], v148 offset:52224
	ds_read_b128 v[204:207], v148 offset:53248
	ds_read_b128 v[208:211], v148 offset:54272
	ds_read_b128 v[212:215], v148 offset:55296
	ds_read_b128 v[216:219], v148 offset:56320
	global_load_lds_dwordx4 v[220:221], off
	s_add_i32 m0, s54, 0x2000
	s_add_u32 s52, s52, 0x40080
	v_lshl_add_u64 v[220:221], v[222:223], 0, s[26:27]
	s_addc_u32 s53, s53, 0
	s_add_i32 s54, s85, s57
	global_load_lds_dwordx4 v[220:221], off
	v_lshl_add_u64 v[220:221], s[52:53], 0, v[0:1]
	s_mov_b32 m0, s54
	s_nop 0
	global_load_lds_dwordx4 v[220:221], off
	v_lshl_add_u64 v[220:221], s[52:53], 0, v[132:133]
	s_add_i32 m0, s54, 0x2000
	s_nop 0
	global_load_lds_dwordx4 v[220:221], off
	v_lshl_add_u64 v[220:221], v[224:225], 0, s[26:27]
	s_mov_b32 m0, s69
	s_nop 0
	global_load_lds_dwordx4 v[220:221], off
	v_lshl_add_u64 v[220:221], v[226:227], 0, s[26:27]
	s_mov_b32 m0, s70
	s_nop 0
	global_load_lds_dwordx4 v[220:221], off
	s_waitcnt vmcnt(8)
	s_waitcnt lgkmcnt(0)
	s_barrier
	s_setprio 1
	s_waitcnt lgkmcnt(0)
	v_mfma_f32_16x16x32_bf16 v[62:65], v[142:145], v[178:181], v[62:65]
	v_mfma_f32_16x16x32_bf16 v[58:61], v[154:157], v[178:181], v[58:61]
	v_mfma_f32_16x16x32_bf16 v[46:49], v[142:145], v[196:199], v[46:49]
	v_mfma_f32_16x16x32_bf16 v[42:45], v[154:157], v[196:199], v[42:45]
	v_mfma_f32_16x16x32_bf16 v[30:33], v[142:145], v[204:207], v[30:33]
	v_mfma_f32_16x16x32_bf16 v[26:29], v[154:157], v[204:207], v[26:29]
	v_mfma_f32_16x16x32_bf16 v[14:17], v[142:145], v[212:215], v[14:17]
	v_mfma_f32_16x16x32_bf16 v[10:13], v[154:157], v[212:215], v[10:13]
	v_mfma_f32_16x16x32_bf16 v[62:65], v[150:153], v[182:185], v[62:65]
	v_mfma_f32_16x16x32_bf16 v[58:61], v[158:161], v[182:185], v[58:61]
	v_mfma_f32_16x16x32_bf16 v[46:49], v[150:153], v[200:203], v[46:49]
	v_mfma_f32_16x16x32_bf16 v[42:45], v[158:161], v[200:203], v[42:45]
	v_mfma_f32_16x16x32_bf16 v[30:33], v[150:153], v[208:211], v[30:33]
	v_mfma_f32_16x16x32_bf16 v[26:29], v[158:161], v[208:211], v[26:29]
	v_mfma_f32_16x16x32_bf16 v[14:17], v[150:153], v[216:219], v[14:17]
	v_mfma_f32_16x16x32_bf16 v[10:13], v[158:161], v[216:219], v[10:13]
	s_setprio 0
	s_setprio 1
	v_mfma_f32_16x16x32_bf16 v[54:57], v[162:165], v[178:181], v[54:57]
	v_mfma_f32_16x16x32_bf16 v[50:53], v[170:173], v[178:181], v[50:53]
	v_mfma_f32_16x16x32_bf16 v[38:41], v[162:165], v[196:199], v[38:41]
	v_mfma_f32_16x16x32_bf16 v[34:37], v[170:173], v[196:199], v[34:37]
	v_mfma_f32_16x16x32_bf16 v[22:25], v[162:165], v[204:207], v[22:25]
	v_mfma_f32_16x16x32_bf16 v[18:21], v[170:173], v[204:207], v[18:21]
	v_mfma_f32_16x16x32_bf16 v[6:9], v[162:165], v[212:215], v[6:9]
	v_mfma_f32_16x16x32_bf16 v[2:5], v[170:173], v[212:215], v[2:5]
	v_mfma_f32_16x16x32_bf16 v[54:57], v[166:169], v[182:185], v[54:57]
	v_mfma_f32_16x16x32_bf16 v[50:53], v[174:177], v[182:185], v[50:53]
	v_mfma_f32_16x16x32_bf16 v[38:41], v[166:169], v[200:203], v[38:41]
	v_mfma_f32_16x16x32_bf16 v[34:37], v[174:177], v[200:203], v[34:37]
	v_mfma_f32_16x16x32_bf16 v[22:25], v[166:169], v[208:211], v[22:25]
	v_mfma_f32_16x16x32_bf16 v[18:21], v[174:177], v[208:211], v[18:21]
	v_mfma_f32_16x16x32_bf16 v[6:9], v[166:169], v[216:219], v[6:9]
	v_mfma_f32_16x16x32_bf16 v[2:5], v[174:177], v[216:219], v[2:5]
	s_setprio 0
	s_barrier
	s_add_i32 s83, s83, 2
	s_add_u32 s50, s50, 0x100
	s_addc_u32 s51, s51, 0
	s_add_u32 s81, s81, 0x100
	s_addc_u32 s82, s82, 0
	s_cmp_gt_u32 s83, 13

;     __device__ __forceinline__ bool next(int i, Unit& u) const { if (i >= n) return false; int o = own; asm volatile("" : "+s"(o)); u.pm = swap ? i : o; u.pn = swap ? o : i; u.idx = i; return true; }
; #define PG8_STAGE(bufoff, gbase, voff) do { _Pragma("unroll") for (int _i = 0; _i < 2; ++_i) \
;         __builtin_amdgcn_global_load_lds((const unsigned*)((const char*)(gbase) + (voff)[_i]), (PG8_LAS unsigned*)(lds + (bufoff) + ldsw + _i * 8192), 16, 0, 0); } while (0)
; template <class Epi, class Sched, bool ALIGN_EPI = false, bool SP2 = false>
; __device__ __forceinline__ void gemm_phase(PG8_LAS unsigned char* lds, const Gemm g, const Sched& S, const Epi& E, int tid_in) {
;     ...
;         const bool has_next = S.next(ui + 1, nxt);
;         const char* nA = has_next ? (const char*)g.A + (size_t)nxt.pm * tstep : cA; const char* nB = has_next ? (const char*)g.Bt + (size_t)nxt.pn * tstep : cB;
;         for (int t = 0; t < nt; t += 2) {
;             const bool last = (t == nt - 2);
;             const char* a1 = cA + (size_t)(t + 1) * kstep;
;             const char* a2 = last ? nA : cA + (size_t)(t + 2) * kstep; const char* b2 = last ? nB : cB + (size_t)(t + 2) * kstep;
;             const char* a3 = a2 + kstep; const char* b3 = b2 + kstep;
;             if (last && has_next) S.a_ready(nxt);
;             if constexpr (SP2) {
;             PG8_LDB(B0, 0, 0); PG8_LDB(B1, 0, 1); PG8_SCHED; PG8_LDA(At, 0, 0); PG8_STAGE(PG8_SA(1, 1), a1 + hstep, voffA);
;             PG8_WAIT_V(8); PG8_WAIT_L(0); PG8_BAR; PG8_MMA(0, 0, At, B0); PG8_MMA(0, 1, At, B1); PG8_BAR; PG8_SCHED;
;             PG8_LDA(At, 0, 1); PG8_STAGE(PG8_SB(0, 0), b2, voffB); PG8_STAGE(PG8_SB(0, 1), b2 + hstep, voffB); PG8_STAGE(PG8_SA(0, 0), a2, voffA);
;             PG8_WAIT_V(8); PG8_WAIT_L(0); PG8_BAR; PG8_MMA(1, 0, At, B0); PG8_MMA(1, 1, At, B1); PG8_BAR; PG8_SCHED;
;             PG8_LDB(B0, 1, 0); PG8_LDB(B1, 1, 1); PG8_SCHED; PG8_LDA(At, 1, 0); PG8_STAGE(PG8_SA(0, 1), a2 + hstep, voffA);
;             PG8_WAIT_V(8); PG8_WAIT_L(0); PG8_BAR; PG8_MMA(0, 0, At, B0); PG8_MMA(0, 1, At, B1); PG8_BAR; PG8_SCHED;
;             PG8_LDA(At, 1, 1); PG8_STAGE(PG8_SB(1, 0), b3, voffB); PG8_STAGE(PG8_SB(1, 1), b3 + hstep, voffB); PG8_STAGE(PG8_SA(1, 0), a3, voffA);
;             PG8_WAIT_V(8); PG8_WAIT_L(0); PG8_BAR; PG8_MMA(1, 0, At, B0); PG8_MMA(1, 1, At, B1); PG8_BAR; PG8_SCHED;
.LBB0_205:
	s_ashr_i32 s45, s44, 31
	s_lshl_b64 s[46:47], s[44:45], 19
	s_add_u32 s46, s28, s46
	s_addc_u32 s47, s29, s47
	s_and_b64 s[48:49], s[52:53], exec
	s_cselect_b32 s45, s47, s57
	s_cselect_b32 s76, s46, s56
	s_ashr_i32 s43, s42, 31
	s_lshl_b64 s[48:49], s[42:43], 19
	s_add_u32 s48, s59, s48
	s_addc_u32 s49, s60, s49
	s_and_b64 s[52:53], s[52:53], exec
	s_cselect_b32 s43, s49, s55
	s_cselect_b32 s77, s48, s54
	s_add_u32 s52, s56, 0x40080
	s_addc_u32 s53, s57, 0
	s_add_u32 s78, s54, 0x100
	s_addc_u32 s79, s55, 0
	s_mov_b32 s80, -2
	s_add_u32 s33, s52, 0xfffc0080
	s_addc_u32 s54, s53, -1
	s_add_i32 s84, 0, 0x10000
	s_cmp_eq_u32 s80, 12
	s_cselect_b32 s57, s45, s54
	s_cselect_b32 s56, s76, s33
	s_cselect_b32 s55, s43, s79
	s_cselect_b32 s54, s77, s78
	s_add_i32 s85, 0, 0x14000
	v_add_u32_e32 v142, s84, v162
	v_add_u32_e32 v172, s85, v162
	ds_read_b128 v[130:133], v142
	ds_read_b128 v[134:137], v142 offset:1024
	ds_read_b128 v[138:141], v142 offset:2048
	ds_read_b128 v[142:145], v142 offset:3072
	ds_read_b128 v[156:159], v172
	ds_read_b128 v[164:167], v172 offset:1024
	ds_read_b128 v[168:171], v172 offset:2048
	ds_read_b128 v[172:175], v172 offset:3072
	v_lshl_add_u64 v[184:185], s[52:53], 0, v[152:153]
	s_add_i32 m0, s62, 0xc000
	ds_read_b128 v[176:179], v163
	ds_read_b128 v[180:183], v163 offset:1024
	ds_read_b128 v[196:199], v163 offset:2048
	ds_read_b128 v[200:203], v163 offset:3072
	ds_read_b128 v[204:207], v163 offset:4096
	ds_read_b128 v[208:211], v163 offset:5120
	ds_read_b128 v[212:215], v163 offset:6144
	ds_read_b128 v[216:219], v163 offset:7168
	global_load_lds_dwordx4 v[184:185], off
	v_lshl_add_u64 v[184:185], s[52:53], 0, v[154:155]
	s_add_i32 m0, s62, 0xe000
	s_nop 0
	global_load_lds_dwordx4 v[184:185], off
	s_waitcnt vmcnt(8)
	s_waitcnt lgkmcnt(0)
	s_barrier
	s_setprio 1
	s_waitcnt lgkmcnt(0)
	v_mfma_f32_16x16x32_bf16 v[126:129], v[130:133], v[176:179], 0
	v_mfma_f32_16x16x32_bf16 v[122:125], v[138:141], v[176:179], 0
	v_mfma_f32_16x16x32_bf16 v[110:113], v[130:133], v[196:199], 0
	v_mfma_f32_16x16x32_bf16 v[106:109], v[138:141], v[196:199], 0
	v_mfma_f32_16x16x32_bf16 v[94:97], v[130:133], v[204:207], 0
	v_mfma_f32_16x16x32_bf16 v[90:93], v[138:141], v[204:207], 0
	v_mfma_f32_16x16x32_bf16 v[78:81], v[130:133], v[212:215], 0
	v_mfma_f32_16x16x32_bf16 v[74:77], v[138:141], v[212:215], 0
	v_mfma_f32_16x16x32_bf16 v[126:129], v[134:137], v[180:183], v[126:129]
	v_mfma_f32_16x16x32_bf16 v[122:125], v[142:145], v[180:183], v[122:125]
	v_mfma_f32_16x16x32_bf16 v[110:113], v[134:137], v[200:203], v[110:113]
	v_mfma_f32_16x16x32_bf16 v[106:109], v[142:145], v[200:203], v[106:109]
	v_mfma_f32_16x16x32_bf16 v[94:97], v[134:137], v[208:211], v[94:97]
	v_mfma_f32_16x16x32_bf16 v[90:93], v[142:145], v[208:211], v[90:93]
	v_mfma_f32_16x16x32_bf16 v[78:81], v[134:137], v[216:219], v[78:81]
	v_mfma_f32_16x16x32_bf16 v[74:77], v[142:145], v[216:219], v[74:77]
	s_setprio 0
	s_setprio 1
	v_mfma_f32_16x16x32_bf16 v[118:121], v[156:159], v[176:179], 0
	v_mfma_f32_16x16x32_bf16 v[114:117], v[168:171], v[176:179], 0
	v_mfma_f32_16x16x32_bf16 v[102:105], v[156:159], v[196:199], 0
	v_mfma_f32_16x16x32_bf16 v[98:101], v[168:171], v[196:199], 0
	v_mfma_f32_16x16x32_bf16 v[86:89], v[156:159], v[204:207], 0
	v_mfma_f32_16x16x32_bf16 v[82:85], v[168:171], v[204:207], 0
	v_mfma_f32_16x16x32_bf16 v[70:73], v[156:159], v[212:215], 0
	v_mfma_f32_16x16x32_bf16 v[66:69], v[168:171], v[212:215], 0
	v_mfma_f32_16x16x32_bf16 v[118:121], v[164:167], v[180:183], v[118:121]
	v_mfma_f32_16x16x32_bf16 v[114:117], v[172:175], v[180:183], v[114:117]
	v_mfma_f32_16x16x32_bf16 v[102:105], v[164:167], v[200:203], v[102:105]
	v_mfma_f32_16x16x32_bf16 v[98:101], v[172:175], v[200:203], v[98:101]
	v_mfma_f32_16x16x32_bf16 v[86:89], v[164:167], v[208:211], v[86:89]
	v_mfma_f32_16x16x32_bf16 v[82:85], v[172:175], v[208:211], v[82:85]
	v_mfma_f32_16x16x32_bf16 v[70:73], v[164:167], v[216:219], v[70:73]
	v_mfma_f32_16x16x32_bf16 v[66:69], v[172:175], v[216:219], v[66:69]
	s_setprio 0
	s_barrier
	s_add_i32 s33, s84, s61
	v_lshl_add_u64 v[184:185], s[54:55], 0, v[0:1]
	s_mov_b32 m0, s33
	ds_read_b128 v[176:179], v163 offset:16384
	ds_read_b128 v[180:183], v163 offset:17408
	ds_read_b128 v[196:199], v163 offset:18432
	ds_read_b128 v[200:203], v163 offset:19456
	ds_read_b128 v[204:207], v163 offset:20480
	ds_read_b128 v[208:211], v163 offset:21504
	ds_read_b128 v[212:215], v163 offset:22528
	ds_read_b128 v[216:219], v163 offset:23552
	global_load_lds_dwordx4 v[184:185], off
	s_add_i32 m0, s33, 0x2000
	s_add_u32 s82, s54, 0x40000
	v_lshl_add_u64 v[220:221], s[54:55], 0, v[146:147]
	s_addc_u32 s83, s55, 0
	s_add_i32 s33, s85, s61
	global_load_lds_dwordx4 v[220:221], off
	v_lshl_add_u64 v[222:223], s[82:83], 0, v[0:1]
	s_mov_b32 m0, s33
	v_lshl_add_u64 v[224:225], s[56:57], 0, v[148:149]
	global_load_lds_dwordx4 v[222:223], off
	v_lshl_add_u64 v[222:223], s[82:83], 0, v[146:147]
	s_add_i32 m0, s33, 0x2000
	s_nop 0
	global_load_lds_dwordx4 v[222:223], off
	v_lshl_add_u64 v[222:223], s[56:57], 0, v[150:151]
	s_mov_b32 m0, s62
	s_nop 0
	global_load_lds_dwordx4 v[222:223], off
	s_mov_b32 m0, s63
	s_nop 0
	global_load_lds_dwordx4 v[224:225], off
	s_waitcnt vmcnt(8)
	s_waitcnt lgkmcnt(0)
	s_barrier
; #define PG8_STAGE(bufoff, gbase, voff) do { _Pragma("unroll") for (int _i = 0; _i < 2; ++_i) \
;         __builtin_amdgcn_global_load_lds((const unsigned*)((const char*)(gbase) + (voff)[_i]), (PG8_LAS unsigned*)(lds + (bufoff) + ldsw + _i * 8192), 16, 0, 0); } while (0)
; #define PG8_LDA(dst, b, h) do { _Pragma("unroll") for (int m = 0; m < 4; ++m) _Pragma("unroll") for (int k = 0; k < 2; ++k) dst[m][k] = *(const PG8_LAS bf16x8*)(lds + PG8_SA(b, h) + aoff + m * 2048 + k * 1024); } while (0)
; #define PG8_LDB(dst, b, h) do { _Pragma("unroll") for (int n = 0; n < 2; ++n) _Pragma("unroll") for (int k = 0; k < 2; ++k) dst[n][k] = *(const PG8_LAS bf16x8*)(lds + PG8_SB(b, h) + boff + n * 2048 + k * 1024); } while (0)
; #define PG8_MMA(ai, bj, At, Bt) do { __builtin_amdgcn_s_setprio(1); _Pragma("unroll") for (int k = 0; k < 2; ++k) _Pragma("unroll") for (int m = 0; m < 4; ++m) _Pragma("unroll") for (int n = 0; n < 2; ++n) \
;         acc[ai][bj][m][n] = __builtin_amdgcn_mfma_f32_16x16x32_bf16(Bt[n][k], At[m][k], acc[ai][bj][m][n], 0, 0, 0); __builtin_amdgcn_s_setprio(0); } while (0)
; #define PG8_WAIT_V(n) asm volatile("s_waitcnt vmcnt(" #n ")" ::: "memory")
; #define PG8_WAIT_L(n) asm volatile("s_waitcnt lgkmcnt(" #n ")" ::: "memory")
; template <class Epi, class Sched, bool ALIGN_EPI = false, bool SP2 = false>
; __device__ __forceinline__ void gemm_phase(PG8_LAS unsigned char* lds, const Gemm g, const Sched& S, const Epi& E, int tid_in) {
;     ...
;             PG8_WAIT_V(8); PG8_WAIT_L(0); PG8_BAR; PG8_MMA(0, 0, At, B0); PG8_MMA(0, 1, At, B1); PG8_BAR; PG8_SCHED;
;             PG8_LDA(At, 0, 1); PG8_STAGE(PG8_SB(0, 0), b2, voffB); PG8_STAGE(PG8_SB(0, 1), b2 + hstep, voffB); PG8_STAGE(PG8_SA(0, 0), a2, voffA);
;             PG8_WAIT_V(8); PG8_WAIT_L(0); PG8_BAR; PG8_MMA(1, 0, At, B0); PG8_MMA(1, 1, At, B1); PG8_BAR; PG8_SCHED;
;             PG8_LDB(B0, 1, 0); PG8_LDB(B1, 1, 1); PG8_SCHED; PG8_LDA(At, 1, 0); PG8_STAGE(PG8_SA(0, 1), a2 + hstep, voffA);
;             PG8_WAIT_V(8); PG8_WAIT_L(0); PG8_BAR; PG8_MMA(0, 0, At, B0); PG8_MMA(0, 1, At, B1); PG8_BAR; PG8_SCHED;
;             PG8_LDA(At, 1, 1); PG8_STAGE(PG8_SB(1, 0), b3, voffB); PG8_STAGE(PG8_SB(1, 1), b3 + hstep, voffB); PG8_STAGE(PG8_SA(1, 0), a3, voffA);
;             PG8_WAIT_V(8); PG8_WAIT_L(0); PG8_BAR; PG8_MMA(1, 0, At, B0); PG8_MMA(1, 1, At, B1); PG8_BAR; PG8_SCHED;
	s_setprio 1
	s_waitcnt lgkmcnt(0)
	v_mfma_f32_16x16x32_bf16 v[62:65], v[130:133], v[176:179], 0
	v_mfma_f32_16x16x32_bf16 v[58:61], v[138:141], v[176:179], 0
	v_mfma_f32_16x16x32_bf16 v[46:49], v[130:133], v[196:199], 0
	v_mfma_f32_16x16x32_bf16 v[42:45], v[138:141], v[196:199], 0
	v_mfma_f32_16x16x32_bf16 v[30:33], v[130:133], v[204:207], 0
	v_mfma_f32_16x16x32_bf16 v[26:29], v[138:141], v[204:207], 0
	v_mfma_f32_16x16x32_bf16 v[14:17], v[130:133], v[212:215], 0
	v_mfma_f32_16x16x32_bf16 v[10:13], v[138:141], v[212:215], 0
	v_mfma_f32_16x16x32_bf16 v[62:65], v[134:137], v[180:183], v[62:65]
	v_mfma_f32_16x16x32_bf16 v[58:61], v[142:145], v[180:183], v[58:61]
	v_mfma_f32_16x16x32_bf16 v[46:49], v[134:137], v[200:203], v[46:49]
	v_mfma_f32_16x16x32_bf16 v[42:45], v[142:145], v[200:203], v[42:45]
	v_mfma_f32_16x16x32_bf16 v[30:33], v[134:137], v[208:211], v[30:33]
	v_mfma_f32_16x16x32_bf16 v[26:29], v[142:145], v[208:211], v[26:29]
	v_mfma_f32_16x16x32_bf16 v[14:17], v[134:137], v[216:219], v[14:17]
	v_mfma_f32_16x16x32_bf16 v[10:13], v[142:145], v[216:219], v[10:13]
	s_setprio 0
	s_setprio 1
	v_mfma_f32_16x16x32_bf16 v[54:57], v[156:159], v[176:179], 0
	v_mfma_f32_16x16x32_bf16 v[50:53], v[168:171], v[176:179], 0
	v_mfma_f32_16x16x32_bf16 v[38:41], v[156:159], v[196:199], 0
	v_mfma_f32_16x16x32_bf16 v[34:37], v[168:171], v[196:199], 0
	v_mfma_f32_16x16x32_bf16 v[22:25], v[156:159], v[204:207], 0
	v_mfma_f32_16x16x32_bf16 v[18:21], v[168:171], v[204:207], 0
	v_mfma_f32_16x16x32_bf16 v[6:9], v[156:159], v[212:215], 0
	v_mfma_f32_16x16x32_bf16 v[2:5], v[168:171], v[212:215], 0
	v_mfma_f32_16x16x32_bf16 v[54:57], v[164:167], v[180:183], v[54:57]
	v_mfma_f32_16x16x32_bf16 v[50:53], v[172:175], v[180:183], v[50:53]
	v_mfma_f32_16x16x32_bf16 v[38:41], v[164:167], v[200:203], v[38:41]
	v_mfma_f32_16x16x32_bf16 v[34:37], v[172:175], v[200:203], v[34:37]
	v_mfma_f32_16x16x32_bf16 v[22:25], v[164:167], v[208:211], v[22:25]
	v_mfma_f32_16x16x32_bf16 v[18:21], v[172:175], v[208:211], v[18:21]
	v_mfma_f32_16x16x32_bf16 v[6:9], v[164:167], v[216:219], v[6:9]
	v_mfma_f32_16x16x32_bf16 v[2:5], v[172:175], v[216:219], v[2:5]
	s_setprio 0
	s_barrier
	s_add_i32 s33, 0, 0x18000
	s_add_i32 s74, 0, 0x1c000
	v_add_u32_e32 v142, s33, v162
	v_add_u32_e32 v172, s74, v162
	ds_read_b128 v[130:133], v142
	ds_read_b128 v[134:137], v142 offset:1024
	ds_read_b128 v[138:141], v142 offset:2048
	ds_read_b128 v[142:145], v142 offset:3072
	ds_read_b128 v[156:159], v172
	ds_read_b128 v[164:167], v172 offset:1024
	ds_read_b128 v[168:171], v172 offset:2048
	ds_read_b128 v[172:175], v172 offset:3072
	s_add_u32 s56, s56, 0x40000
	s_addc_u32 s57, s57, 0
	s_mov_b32 m0, s64
	v_lshl_add_u64 v[226:227], s[56:57], 0, v[150:151]
	ds_read_b128 v[176:179], v163 offset:32768
	ds_read_b128 v[180:183], v163 offset:33792
	ds_read_b128 v[196:199], v163 offset:34816
	ds_read_b128 v[200:203], v163 offset:35840
	ds_read_b128 v[204:207], v163 offset:36864
	ds_read_b128 v[208:211], v163 offset:37888
	ds_read_b128 v[212:215], v163 offset:38912
	ds_read_b128 v[216:219], v163 offset:39936
	global_load_lds_dwordx4 v[226:227], off
	v_lshl_add_u64 v[226:227], s[56:57], 0, v[148:149]
	s_mov_b32 m0, s65
	s_nop 0
	global_load_lds_dwordx4 v[226:227], off
	s_waitcnt vmcnt(8)
	s_waitcnt lgkmcnt(0)
	s_barrier
	s_setprio 1
	s_waitcnt lgkmcnt(0)
	v_mfma_f32_16x16x32_bf16 v[126:129], v[130:133], v[176:179], v[126:129]
	v_mfma_f32_16x16x32_bf16 v[122:125], v[138:141], v[176:179], v[122:125]
	v_mfma_f32_16x16x32_bf16 v[110:113], v[130:133], v[196:199], v[110:113]
	v_mfma_f32_16x16x32_bf16 v[106:109], v[138:141], v[196:199], v[106:109]
	v_mfma_f32_16x16x32_bf16 v[94:97], v[130:133], v[204:207], v[94:97]
	v_mfma_f32_16x16x32_bf16 v[90:93], v[138:141], v[204:207], v[90:93]
	v_mfma_f32_16x16x32_bf16 v[78:81], v[130:133], v[212:215], v[78:81]
	v_mfma_f32_16x16x32_bf16 v[74:77], v[138:141], v[212:215], v[74:77]
	v_mfma_f32_16x16x32_bf16 v[126:129], v[134:137], v[180:183], v[126:129]
	v_mfma_f32_16x16x32_bf16 v[122:125], v[142:145], v[180:183], v[122:125]
	v_mfma_f32_16x16x32_bf16 v[110:113], v[134:137], v[200:203], v[110:113]
	v_mfma_f32_16x16x32_bf16 v[106:109], v[142:145], v[200:203], v[106:109]
	v_mfma_f32_16x16x32_bf16 v[94:97], v[134:137], v[208:211], v[94:97]
	v_mfma_f32_16x16x32_bf16 v[90:93], v[142:145], v[208:211], v[90:93]
	v_mfma_f32_16x16x32_bf16 v[78:81], v[134:137], v[216:219], v[78:81]
	v_mfma_f32_16x16x32_bf16 v[74:77], v[142:145], v[216:219], v[74:77]
	s_setprio 0
	s_setprio 1
	v_mfma_f32_16x16x32_bf16 v[118:121], v[156:159], v[176:179], v[118:121]
	v_mfma_f32_16x16x32_bf16 v[114:117], v[168:171], v[176:179], v[114:117]
	v_mfma_f32_16x16x32_bf16 v[102:105], v[156:159], v[196:199], v[102:105]
	v_mfma_f32_16x16x32_bf16 v[98:101], v[168:171], v[196:199], v[98:101]
	v_mfma_f32_16x16x32_bf16 v[86:89], v[156:159], v[204:207], v[86:89]
	v_mfma_f32_16x16x32_bf16 v[82:85], v[168:171], v[204:207], v[82:85]
	v_mfma_f32_16x16x32_bf16 v[70:73], v[156:159], v[212:215], v[70:73]
	v_mfma_f32_16x16x32_bf16 v[66:69], v[168:171], v[212:215], v[66:69]
	v_mfma_f32_16x16x32_bf16 v[118:121], v[164:167], v[180:183], v[118:121]
	v_mfma_f32_16x16x32_bf16 v[114:117], v[172:175], v[180:183], v[114:117]
	v_mfma_f32_16x16x32_bf16 v[102:105], v[164:167], v[200:203], v[102:105]
	v_mfma_f32_16x16x32_bf16 v[98:101], v[172:175], v[200:203], v[98:101]
	v_mfma_f32_16x16x32_bf16 v[86:89], v[164:167], v[208:211], v[86:89]
	v_mfma_f32_16x16x32_bf16 v[82:85], v[172:175], v[208:211], v[82:85]
	v_mfma_f32_16x16x32_bf16 v[70:73], v[164:167], v[216:219], v[70:73]
	v_mfma_f32_16x16x32_bf16 v[66:69], v[172:175], v[216:219], v[66:69]
	s_setprio 0
	s_barrier
; #define PG8_STAGE(bufoff, gbase, voff) do { _Pragma("unroll") for (int _i = 0; _i < 2; ++_i) \
;         __builtin_amdgcn_global_load_lds((const unsigned*)((const char*)(gbase) + (voff)[_i]), (PG8_LAS unsigned*)(lds + (bufoff) + ldsw + _i * 8192), 16, 0, 0); } while (0)
; #define PG8_LDA(dst, b, h) do { _Pragma("unroll") for (int m = 0; m < 4; ++m) _Pragma("unroll") for (int k = 0; k < 2; ++k) dst[m][k] = *(const PG8_LAS bf16x8*)(lds + PG8_SA(b, h) + aoff + m * 2048 + k * 1024); } while (0)
; #define PG8_MMA(ai, bj, At, Bt) do { __builtin_amdgcn_s_setprio(1); _Pragma("unroll") for (int k = 0; k < 2; ++k) _Pragma("unroll") for (int m = 0; m < 4; ++m) _Pragma("unroll") for (int n = 0; n < 2; ++n) \
;         acc[ai][bj][m][n] = __builtin_amdgcn_mfma_f32_16x16x32_bf16(Bt[n][k], At[m][k], acc[ai][bj][m][n], 0, 0, 0); __builtin_amdgcn_s_setprio(0); } while (0)
; #define PG8_WAIT_V(n) asm volatile("s_waitcnt vmcnt(" #n ")" ::: "memory")
; #define PG8_WAIT_L(n) asm volatile("s_waitcnt lgkmcnt(" #n ")" ::: "memory")
; #define PG8_BAR __builtin_amdgcn_s_barrier()
; #define PG8_SCHED __builtin_amdgcn_sched_barrier(0)
; template <class Epi, class Sched, bool ALIGN_EPI = false, bool SP2 = false>
; __device__ __forceinline__ void gemm_phase(PG8_LAS unsigned char* lds, const Gemm g, const Sched& S, const Epi& E, int tid_in) {
;     ...
;         for (int t = 0; t < nt; t += 2) {
;     ...
;             PG8_LDA(At, 1, 1); PG8_STAGE(PG8_SB(1, 0), b3, voffB); PG8_STAGE(PG8_SB(1, 1), b3 + hstep, voffB); PG8_STAGE(PG8_SA(1, 0), a3, voffA);
;             PG8_WAIT_V(8); PG8_WAIT_L(0); PG8_BAR; PG8_MMA(1, 0, At, B0); PG8_MMA(1, 1, At, B1); PG8_BAR; PG8_SCHED;
	s_add_i32 s56, s33, s61
	v_lshl_add_u64 v[184:185], v[184:185], 0, s[26:27]
	s_mov_b32 m0, s56
	ds_read_b128 v[176:179], v163 offset:49152
	ds_read_b128 v[180:183], v163 offset:50176
	ds_read_b128 v[196:199], v163 offset:51200
	ds_read_b128 v[200:203], v163 offset:52224
	ds_read_b128 v[204:207], v163 offset:53248
	ds_read_b128 v[208:211], v163 offset:54272
	ds_read_b128 v[212:215], v163 offset:55296
	ds_read_b128 v[216:219], v163 offset:56320
	global_load_lds_dwordx4 v[184:185], off
	s_add_i32 m0, s56, 0x2000
	s_add_u32 s54, s54, 0x40080
	v_lshl_add_u64 v[184:185], v[220:221], 0, s[26:27]
	s_addc_u32 s55, s55, 0
	s_add_i32 s56, s74, s61
	global_load_lds_dwordx4 v[184:185], off
	v_lshl_add_u64 v[184:185], s[54:55], 0, v[0:1]
	s_mov_b32 m0, s56
	s_nop 0
	global_load_lds_dwordx4 v[184:185], off
	v_lshl_add_u64 v[184:185], s[54:55], 0, v[146:147]
	s_add_i32 m0, s56, 0x2000
	s_nop 0
	global_load_lds_dwordx4 v[184:185], off
	v_lshl_add_u64 v[184:185], v[222:223], 0, s[26:27]
	s_mov_b32 m0, s70
	s_nop 0
	global_load_lds_dwordx4 v[184:185], off
	v_lshl_add_u64 v[184:185], v[224:225], 0, s[26:27]
	s_mov_b32 m0, s75
	s_nop 0
	global_load_lds_dwordx4 v[184:185], off
	s_waitcnt vmcnt(8)
	s_waitcnt lgkmcnt(0)
	s_barrier
	s_setprio 1
	s_waitcnt lgkmcnt(0)
	v_mfma_f32_16x16x32_bf16 v[62:65], v[130:133], v[176:179], v[62:65]
	v_mfma_f32_16x16x32_bf16 v[58:61], v[138:141], v[176:179], v[58:61]
	v_mfma_f32_16x16x32_bf16 v[46:49], v[130:133], v[196:199], v[46:49]
	v_mfma_f32_16x16x32_bf16 v[42:45], v[138:141], v[196:199], v[42:45]
	v_mfma_f32_16x16x32_bf16 v[30:33], v[130:133], v[204:207], v[30:33]
	v_mfma_f32_16x16x32_bf16 v[26:29], v[138:141], v[204:207], v[26:29]
	v_mfma_f32_16x16x32_bf16 v[14:17], v[130:133], v[212:215], v[14:17]
	v_mfma_f32_16x16x32_bf16 v[10:13], v[138:141], v[212:215], v[10:13]
	v_mfma_f32_16x16x32_bf16 v[62:65], v[134:137], v[180:183], v[62:65]
	v_mfma_f32_16x16x32_bf16 v[58:61], v[142:145], v[180:183], v[58:61]
	v_mfma_f32_16x16x32_bf16 v[46:49], v[134:137], v[200:203], v[46:49]
	v_mfma_f32_16x16x32_bf16 v[42:45], v[142:145], v[200:203], v[42:45]
	v_mfma_f32_16x16x32_bf16 v[30:33], v[134:137], v[208:211], v[30:33]
	v_mfma_f32_16x16x32_bf16 v[26:29], v[142:145], v[208:211], v[26:29]
	v_mfma_f32_16x16x32_bf16 v[14:17], v[134:137], v[216:219], v[14:17]
	v_mfma_f32_16x16x32_bf16 v[10:13], v[142:145], v[216:219], v[10:13]
	s_setprio 0
	s_setprio 1
	v_mfma_f32_16x16x32_bf16 v[54:57], v[156:159], v[176:179], v[54:57]
	v_mfma_f32_16x16x32_bf16 v[50:53], v[168:171], v[176:179], v[50:53]
	v_mfma_f32_16x16x32_bf16 v[38:41], v[156:159], v[196:199], v[38:41]
	v_mfma_f32_16x16x32_bf16 v[34:37], v[168:171], v[196:199], v[34:37]
	v_mfma_f32_16x16x32_bf16 v[22:25], v[156:159], v[204:207], v[22:25]
	v_mfma_f32_16x16x32_bf16 v[18:21], v[168:171], v[204:207], v[18:21]
	v_mfma_f32_16x16x32_bf16 v[6:9], v[156:159], v[212:215], v[6:9]
	v_mfma_f32_16x16x32_bf16 v[2:5], v[168:171], v[212:215], v[2:5]
	v_mfma_f32_16x16x32_bf16 v[54:57], v[164:167], v[180:183], v[54:57]
	v_mfma_f32_16x16x32_bf16 v[50:53], v[172:175], v[180:183], v[50:53]
	v_mfma_f32_16x16x32_bf16 v[38:41], v[164:167], v[200:203], v[38:41]
	v_mfma_f32_16x16x32_bf16 v[34:37], v[172:175], v[200:203], v[34:37]
	v_mfma_f32_16x16x32_bf16 v[22:25], v[164:167], v[208:211], v[22:25]
	v_mfma_f32_16x16x32_bf16 v[18:21], v[172:175], v[208:211], v[18:21]
	v_mfma_f32_16x16x32_bf16 v[6:9], v[164:167], v[216:219], v[6:9]
	v_mfma_f32_16x16x32_bf16 v[2:5], v[172:175], v[216:219], v[2:5]
	s_setprio 0
	s_barrier
	s_add_i32 s80, s80, 2
	s_add_u32 s52, s52, 0x100
	s_addc_u32 s53, s53, 0
	s_add_u32 s78, s78, 0x100
	s_addc_u32 s79, s79, 0
	s_cmp_gt_u32 s80, 13

;     __device__ __forceinline__ bool next(int i, Unit& u) const { if (i >= n) return false; int o = own; asm volatile("" : "+s"(o)); u.pm = swap ? i : o; u.pn = swap ? o : i; u.idx = i; return true; }
; #define PG8_STAGE(bufoff, gbase, voff) do { _Pragma("unroll") for (int _i = 0; _i < 2; ++_i) \
;         __builtin_amdgcn_global_load_lds((const unsigned*)((const char*)(gbase) + (voff)[_i]), (PG8_LAS unsigned*)(lds + (bufoff) + ldsw + _i * 8192), 16, 0, 0); } while (0)
; #define PG8_LDA(dst, b, h) do { _Pragma("unroll") for (int m = 0; m < 4; ++m) _Pragma("unroll") for (int k = 0; k < 2; ++k) dst[m][k] = *(const PG8_LAS bf16x8*)(lds + PG8_SA(b, h) + aoff + m * 2048 + k * 1024); } while (0)
; #define PG8_LDB(dst, b, h) do { _Pragma("unroll") for (int n = 0; n < 2; ++n) _Pragma("unroll") for (int k = 0; k < 2; ++k) dst[n][k] = *(const PG8_LAS bf16x8*)(lds + PG8_SB(b, h) + boff + n * 2048 + k * 1024); } while (0)
; #define PG8_WAIT_V(n) asm volatile("s_waitcnt vmcnt(" #n ")" ::: "memory")
; template <class Epi, class Sched, bool ALIGN_EPI = false, bool SP2 = false>
; __device__ __forceinline__ void gemm_phase(PG8_LAS unsigned char* lds, const Gemm g, const Sched& S, const Epi& E, int tid_in) {
;     ...
;         const bool has_next = S.next(ui + 1, nxt);
;         const char* nA = has_next ? (const char*)g.A + (size_t)nxt.pm * tstep : cA; const char* nB = has_next ? (const char*)g.Bt + (size_t)nxt.pn * tstep : cB;
;         for (int t = 0; t < nt; t += 2) {
;             const bool last = (t == nt - 2);
;             const char* a1 = cA + (size_t)(t + 1) * kstep;
;             const char* a2 = last ? nA : cA + (size_t)(t + 2) * kstep; const char* b2 = last ? nB : cB + (size_t)(t + 2) * kstep;
;             const char* a3 = a2 + kstep; const char* b3 = b2 + kstep;
;             if (last && has_next) S.a_ready(nxt);
;             if constexpr (SP2) {
;             PG8_LDB(B0, 0, 0); PG8_LDB(B1, 0, 1); PG8_SCHED; PG8_LDA(At, 0, 0); PG8_STAGE(PG8_SA(1, 1), a1 + hstep, voffA);
;             PG8_WAIT_V(8); PG8_WAIT_L(0); PG8_BAR; PG8_MMA(0, 0, At, B0); PG8_MMA(0, 1, At, B1); PG8_BAR; PG8_SCHED;
;             PG8_LDA(At, 0, 1); PG8_STAGE(PG8_SB(0, 0), b2, voffB); PG8_STAGE(PG8_SB(0, 1), b2 + hstep, voffB); PG8_STAGE(PG8_SA(0, 0), a2, voffA);
;             PG8_WAIT_V(8); PG8_WAIT_L(0); PG8_BAR; PG8_MMA(1, 0, At, B0); PG8_MMA(1, 1, At, B1); PG8_BAR; PG8_SCHED;
.LBB0_358:
	s_ashr_i32 s51, s50, 31
	s_lshl_b64 s[54:55], s[50:51], 19
	s_add_u32 s54, s68, s54
	s_addc_u32 s55, s69, s55
	s_and_b64 s[56:57], s[48:49], exec
	s_cselect_b32 s51, s55, s59
	s_cselect_b32 s81, s54, s58
	s_ashr_i32 s53, s52, 31
	s_lshl_b64 s[56:57], s[52:53], 19
	s_add_u32 s56, s64, s56
	s_addc_u32 s57, s65, s57
	s_and_b64 s[62:63], s[48:49], exec
	s_cselect_b32 s53, s57, s61
	s_cselect_b32 s82, s56, s60
	s_add_u32 s58, s58, 0x40080
	s_addc_u32 s59, s59, 0
	s_add_u32 s83, s60, 0x100
	s_addc_u32 vcc_lo, s61, 0
	s_mov_b32 vcc_hi, -2
	s_waitcnt vmcnt(0)
	v_add_u32_e32 v142, s84, v214
	v_add_u32_e32 v158, s85, v214
	s_waitcnt lgkmcnt(0)
	ds_read_b128 v[130:133], v142
	ds_read_b128 v[134:137], v142 offset:1024
	ds_read_b128 v[138:141], v142 offset:2048
	ds_read_b128 v[142:145], v142 offset:3072
	ds_read_b128 v[146:149], v158
	ds_read_b128 v[150:153], v158 offset:1024
	ds_read_b128 v[154:157], v158 offset:2048
	ds_read_b128 v[158:161], v158 offset:3072
	s_add_u32 s60, s58, 0xfffc0080
	s_addc_u32 s61, s59, -1
	s_cmp_eq_u32 vcc_hi, 12
	s_cselect_b32 s63, s51, s61
	s_cselect_b32 s62, s81, s60
	s_cselect_b32 s61, s53, vcc_lo
	s_cselect_b32 s60, s82, s83
	v_lshl_add_u64 v[216:217], s[58:59], 0, v[202:203]
	s_add_i32 m0, s76, 0xc000
	ds_read_b128 v[162:165], v215
	ds_read_b128 v[166:169], v215 offset:1024
	ds_read_b128 v[170:173], v215 offset:2048
	ds_read_b128 v[174:177], v215 offset:3072
	ds_read_b128 v[178:181], v215 offset:4096
	ds_read_b128 v[182:185], v215 offset:5120
	ds_read_b128 v[206:209], v215 offset:6144
	ds_read_b128 v[210:213], v215 offset:7168
	global_load_lds_dwordx4 v[216:217], off
	v_lshl_add_u64 v[216:217], s[58:59], 0, v[204:205]
	s_add_i32 m0, s76, 0xe000
	s_nop 0
	global_load_lds_dwordx4 v[216:217], off
	s_waitcnt vmcnt(8)
	s_waitcnt lgkmcnt(0)
	s_barrier
	s_setprio 1
	s_waitcnt lgkmcnt(0)
	v_mfma_f32_16x16x32_bf16 v[126:129], v[130:133], v[162:165], 0
	v_mfma_f32_16x16x32_bf16 v[122:125], v[138:141], v[162:165], 0
	v_mfma_f32_16x16x32_bf16 v[110:113], v[130:133], v[170:173], 0
	v_mfma_f32_16x16x32_bf16 v[106:109], v[138:141], v[170:173], 0
	v_mfma_f32_16x16x32_bf16 v[94:97], v[130:133], v[178:181], 0
	v_mfma_f32_16x16x32_bf16 v[90:93], v[138:141], v[178:181], 0
	v_mfma_f32_16x16x32_bf16 v[78:81], v[130:133], v[206:209], 0
	v_mfma_f32_16x16x32_bf16 v[74:77], v[138:141], v[206:209], 0
	v_mfma_f32_16x16x32_bf16 v[126:129], v[134:137], v[166:169], v[126:129]
	v_mfma_f32_16x16x32_bf16 v[122:125], v[142:145], v[166:169], v[122:125]
	v_mfma_f32_16x16x32_bf16 v[110:113], v[134:137], v[174:177], v[110:113]
	v_mfma_f32_16x16x32_bf16 v[106:109], v[142:145], v[174:177], v[106:109]
	v_mfma_f32_16x16x32_bf16 v[94:97], v[134:137], v[182:185], v[94:97]
	v_mfma_f32_16x16x32_bf16 v[90:93], v[142:145], v[182:185], v[90:93]
	v_mfma_f32_16x16x32_bf16 v[78:81], v[134:137], v[210:213], v[78:81]
	v_mfma_f32_16x16x32_bf16 v[74:77], v[142:145], v[210:213], v[74:77]
	s_setprio 0
	s_setprio 1
	v_mfma_f32_16x16x32_bf16 v[118:121], v[146:149], v[162:165], 0
	v_mfma_f32_16x16x32_bf16 v[114:117], v[154:157], v[162:165], 0
	v_mfma_f32_16x16x32_bf16 v[102:105], v[146:149], v[170:173], 0
	v_mfma_f32_16x16x32_bf16 v[98:101], v[154:157], v[170:173], 0
	v_mfma_f32_16x16x32_bf16 v[86:89], v[146:149], v[178:181], 0
	v_mfma_f32_16x16x32_bf16 v[82:85], v[154:157], v[178:181], 0
	v_mfma_f32_16x16x32_bf16 v[70:73], v[146:149], v[206:209], 0
	v_mfma_f32_16x16x32_bf16 v[66:69], v[154:157], v[206:209], 0
	v_mfma_f32_16x16x32_bf16 v[118:121], v[150:153], v[166:169], v[118:121]
	v_mfma_f32_16x16x32_bf16 v[114:117], v[158:161], v[166:169], v[114:117]
	v_mfma_f32_16x16x32_bf16 v[102:105], v[150:153], v[174:177], v[102:105]
	v_mfma_f32_16x16x32_bf16 v[98:101], v[158:161], v[174:177], v[98:101]
	v_mfma_f32_16x16x32_bf16 v[86:89], v[150:153], v[182:185], v[86:89]
	v_mfma_f32_16x16x32_bf16 v[82:85], v[158:161], v[182:185], v[82:85]
	v_mfma_f32_16x16x32_bf16 v[70:73], v[150:153], v[210:213], v[70:73]
	v_mfma_f32_16x16x32_bf16 v[66:69], v[158:161], v[210:213], v[66:69]
	s_setprio 0
	s_barrier
	s_add_i32 s92, s84, s75
	v_lshl_add_u64 v[216:217], s[60:61], 0, v[0:1]
	s_mov_b32 m0, s92
	ds_read_b128 v[162:165], v215 offset:16384
	ds_read_b128 v[166:169], v215 offset:17408
	ds_read_b128 v[170:173], v215 offset:18432
	ds_read_b128 v[174:177], v215 offset:19456
	ds_read_b128 v[178:181], v215 offset:20480
	ds_read_b128 v[182:185], v215 offset:21504
	ds_read_b128 v[206:209], v215 offset:22528
	ds_read_b128 v[210:213], v215 offset:23552
	global_load_lds_dwordx4 v[216:217], off
	s_add_i32 m0, s92, 0x2000
	s_add_u32 s92, s60, 0x40000
	v_lshl_add_u64 v[218:219], s[60:61], 0, v[196:197]
	s_addc_u32 s93, s61, 0
	s_add_i32 s94, s85, s75
	global_load_lds_dwordx4 v[218:219], off
	v_lshl_add_u64 v[220:221], s[92:93], 0, v[0:1]
	s_mov_b32 m0, s94
	v_lshl_add_u64 v[222:223], s[62:63], 0, v[198:199]
	global_load_lds_dwordx4 v[220:221], off
	v_lshl_add_u64 v[220:221], s[92:93], 0, v[196:197]
	s_add_i32 m0, s94, 0x2000
	s_nop 0
	global_load_lds_dwordx4 v[220:221], off
	v_lshl_add_u64 v[220:221], s[62:63], 0, v[200:201]
	s_mov_b32 m0, s76
	s_nop 0
	global_load_lds_dwordx4 v[220:221], off
	s_mov_b32 m0, s77
	s_nop 0
	global_load_lds_dwordx4 v[222:223], off
	s_waitcnt vmcnt(8)
	s_waitcnt lgkmcnt(0)
	s_barrier
; #define PG8_STAGE(bufoff, gbase, voff) do { _Pragma("unroll") for (int _i = 0; _i < 2; ++_i) \
;         __builtin_amdgcn_global_load_lds((const unsigned*)((const char*)(gbase) + (voff)[_i]), (PG8_LAS unsigned*)(lds + (bufoff) + ldsw + _i * 8192), 16, 0, 0); } while (0)
; #define PG8_LDA(dst, b, h) do { _Pragma("unroll") for (int m = 0; m < 4; ++m) _Pragma("unroll") for (int k = 0; k < 2; ++k) dst[m][k] = *(const PG8_LAS bf16x8*)(lds + PG8_SA(b, h) + aoff + m * 2048 + k * 1024); } while (0)
; #define PG8_LDB(dst, b, h) do { _Pragma("unroll") for (int n = 0; n < 2; ++n) _Pragma("unroll") for (int k = 0; k < 2; ++k) dst[n][k] = *(const PG8_LAS bf16x8*)(lds + PG8_SB(b, h) + boff + n * 2048 + k * 1024); } while (0)
; #define PG8_MMA(ai, bj, At, Bt) do { __builtin_amdgcn_s_setprio(1); _Pragma("unroll") for (int k = 0; k < 2; ++k) _Pragma("unroll") for (int m = 0; m < 4; ++m) _Pragma("unroll") for (int n = 0; n < 2; ++n) \
;         acc[ai][bj][m][n] = __builtin_amdgcn_mfma_f32_16x16x32_bf16(Bt[n][k], At[m][k], acc[ai][bj][m][n], 0, 0, 0); __builtin_amdgcn_s_setprio(0); } while (0)
; #define PG8_WAIT_V(n) asm volatile("s_waitcnt vmcnt(" #n ")" ::: "memory")
; #define PG8_WAIT_L(n) asm volatile("s_waitcnt lgkmcnt(" #n ")" ::: "memory")
; #define PG8_BAR __builtin_amdgcn_s_barrier()
; #define PG8_SCHED __builtin_amdgcn_sched_barrier(0)
; template <class Epi, class Sched, bool ALIGN_EPI = false, bool SP2 = false>
; __device__ __forceinline__ void gemm_phase(PG8_LAS unsigned char* lds, const Gemm g, const Sched& S, const Epi& E, int tid_in) {
;     ...
;             PG8_WAIT_V(8); PG8_WAIT_L(0); PG8_BAR; PG8_MMA(1, 0, At, B0); PG8_MMA(1, 1, At, B1); PG8_BAR; PG8_SCHED;
;             PG8_LDB(B0, 1, 0); PG8_LDB(B1, 1, 1); PG8_SCHED; PG8_LDA(At, 1, 0); PG8_STAGE(PG8_SA(0, 1), a2 + hstep, voffA);
;             PG8_WAIT_V(8); PG8_WAIT_L(0); PG8_BAR; PG8_MMA(0, 0, At, B0); PG8_MMA(0, 1, At, B1); PG8_BAR; PG8_SCHED;
	s_setprio 1
	s_waitcnt lgkmcnt(0)
	v_mfma_f32_16x16x32_bf16 v[62:65], v[130:133], v[162:165], 0
	v_mfma_f32_16x16x32_bf16 v[58:61], v[138:141], v[162:165], 0
	v_mfma_f32_16x16x32_bf16 v[46:49], v[130:133], v[170:173], 0
	v_mfma_f32_16x16x32_bf16 v[42:45], v[138:141], v[170:173], 0
	v_mfma_f32_16x16x32_bf16 v[30:33], v[130:133], v[178:181], 0
	v_mfma_f32_16x16x32_bf16 v[26:29], v[138:141], v[178:181], 0
	v_mfma_f32_16x16x32_bf16 v[14:17], v[130:133], v[206:209], 0
	v_mfma_f32_16x16x32_bf16 v[10:13], v[138:141], v[206:209], 0
	v_mfma_f32_16x16x32_bf16 v[62:65], v[134:137], v[166:169], v[62:65]
	v_mfma_f32_16x16x32_bf16 v[58:61], v[142:145], v[166:169], v[58:61]
	v_mfma_f32_16x16x32_bf16 v[46:49], v[134:137], v[174:177], v[46:49]
	v_mfma_f32_16x16x32_bf16 v[42:45], v[142:145], v[174:177], v[42:45]
	v_mfma_f32_16x16x32_bf16 v[30:33], v[134:137], v[182:185], v[30:33]
	v_mfma_f32_16x16x32_bf16 v[26:29], v[142:145], v[182:185], v[26:29]
	v_mfma_f32_16x16x32_bf16 v[14:17], v[134:137], v[210:213], v[14:17]
	v_mfma_f32_16x16x32_bf16 v[10:13], v[142:145], v[210:213], v[10:13]
	s_setprio 0
	s_setprio 1
	v_mfma_f32_16x16x32_bf16 v[54:57], v[146:149], v[162:165], 0
	v_mfma_f32_16x16x32_bf16 v[50:53], v[154:157], v[162:165], 0
	v_mfma_f32_16x16x32_bf16 v[38:41], v[146:149], v[170:173], 0
	v_mfma_f32_16x16x32_bf16 v[34:37], v[154:157], v[170:173], 0
	v_mfma_f32_16x16x32_bf16 v[22:25], v[146:149], v[178:181], 0
	v_mfma_f32_16x16x32_bf16 v[18:21], v[154:157], v[178:181], 0
	v_mfma_f32_16x16x32_bf16 v[6:9], v[146:149], v[206:209], 0
	v_mfma_f32_16x16x32_bf16 v[2:5], v[154:157], v[206:209], 0
	v_mfma_f32_16x16x32_bf16 v[54:57], v[150:153], v[166:169], v[54:57]
	v_mfma_f32_16x16x32_bf16 v[50:53], v[158:161], v[166:169], v[50:53]
	v_mfma_f32_16x16x32_bf16 v[38:41], v[150:153], v[174:177], v[38:41]
	v_mfma_f32_16x16x32_bf16 v[34:37], v[158:161], v[174:177], v[34:37]
	v_mfma_f32_16x16x32_bf16 v[22:25], v[150:153], v[182:185], v[22:25]
	v_mfma_f32_16x16x32_bf16 v[18:21], v[158:161], v[182:185], v[18:21]
	v_mfma_f32_16x16x32_bf16 v[6:9], v[150:153], v[210:213], v[6:9]
	v_mfma_f32_16x16x32_bf16 v[2:5], v[158:161], v[210:213], v[2:5]
	s_setprio 0
	s_barrier
	v_add_u32_e32 v142, s33, v214
	v_add_u32_e32 v158, s74, v214
	ds_read_b128 v[130:133], v142
	ds_read_b128 v[134:137], v142 offset:1024
	ds_read_b128 v[138:141], v142 offset:2048
	ds_read_b128 v[142:145], v142 offset:3072
	ds_read_b128 v[146:149], v158
	ds_read_b128 v[150:153], v158 offset:1024
	ds_read_b128 v[154:157], v158 offset:2048
	ds_read_b128 v[158:161], v158 offset:3072
	s_add_u32 s62, s62, 0x40000
	s_addc_u32 s63, s63, 0
	s_mov_b32 m0, s78
	v_lshl_add_u64 v[224:225], s[62:63], 0, v[200:201]
	ds_read_b128 v[162:165], v215 offset:32768
	ds_read_b128 v[166:169], v215 offset:33792
	ds_read_b128 v[170:173], v215 offset:34816
	ds_read_b128 v[174:177], v215 offset:35840
	ds_read_b128 v[178:181], v215 offset:36864
	ds_read_b128 v[182:185], v215 offset:37888
	ds_read_b128 v[206:209], v215 offset:38912
	ds_read_b128 v[210:213], v215 offset:39936
	global_load_lds_dwordx4 v[224:225], off
	v_lshl_add_u64 v[224:225], s[62:63], 0, v[198:199]
	s_mov_b32 m0, s79
	s_nop 0
	global_load_lds_dwordx4 v[224:225], off
	s_waitcnt vmcnt(8)
	s_waitcnt lgkmcnt(0)
	s_barrier
	s_setprio 1
	s_waitcnt lgkmcnt(0)
	v_mfma_f32_16x16x32_bf16 v[126:129], v[130:133], v[162:165], v[126:129]
	v_mfma_f32_16x16x32_bf16 v[122:125], v[138:141], v[162:165], v[122:125]
	v_mfma_f32_16x16x32_bf16 v[110:113], v[130:133], v[170:173], v[110:113]
	v_mfma_f32_16x16x32_bf16 v[106:109], v[138:141], v[170:173], v[106:109]
	v_mfma_f32_16x16x32_bf16 v[94:97], v[130:133], v[178:181], v[94:97]
	v_mfma_f32_16x16x32_bf16 v[90:93], v[138:141], v[178:181], v[90:93]
	v_mfma_f32_16x16x32_bf16 v[78:81], v[130:133], v[206:209], v[78:81]
	v_mfma_f32_16x16x32_bf16 v[74:77], v[138:141], v[206:209], v[74:77]
	v_mfma_f32_16x16x32_bf16 v[126:129], v[134:137], v[166:169], v[126:129]
	v_mfma_f32_16x16x32_bf16 v[122:125], v[142:145], v[166:169], v[122:125]
	v_mfma_f32_16x16x32_bf16 v[110:113], v[134:137], v[174:177], v[110:113]
	v_mfma_f32_16x16x32_bf16 v[106:109], v[142:145], v[174:177], v[106:109]
	v_mfma_f32_16x16x32_bf16 v[94:97], v[134:137], v[182:185], v[94:97]
	v_mfma_f32_16x16x32_bf16 v[90:93], v[142:145], v[182:185], v[90:93]
	v_mfma_f32_16x16x32_bf16 v[78:81], v[134:137], v[210:213], v[78:81]
	v_mfma_f32_16x16x32_bf16 v[74:77], v[142:145], v[210:213], v[74:77]
	s_setprio 0
	s_setprio 1
	v_mfma_f32_16x16x32_bf16 v[118:121], v[146:149], v[162:165], v[118:121]
	v_mfma_f32_16x16x32_bf16 v[114:117], v[154:157], v[162:165], v[114:117]
	v_mfma_f32_16x16x32_bf16 v[102:105], v[146:149], v[170:173], v[102:105]
	v_mfma_f32_16x16x32_bf16 v[98:101], v[154:157], v[170:173], v[98:101]
	v_mfma_f32_16x16x32_bf16 v[86:89], v[146:149], v[178:181], v[86:89]
	v_mfma_f32_16x16x32_bf16 v[82:85], v[154:157], v[178:181], v[82:85]
	v_mfma_f32_16x16x32_bf16 v[70:73], v[146:149], v[206:209], v[70:73]
	v_mfma_f32_16x16x32_bf16 v[66:69], v[154:157], v[206:209], v[66:69]
	v_mfma_f32_16x16x32_bf16 v[118:121], v[150:153], v[166:169], v[118:121]
	v_mfma_f32_16x16x32_bf16 v[114:117], v[158:161], v[166:169], v[114:117]
	v_mfma_f32_16x16x32_bf16 v[102:105], v[150:153], v[174:177], v[102:105]
	v_mfma_f32_16x16x32_bf16 v[98:101], v[158:161], v[174:177], v[98:101]
	v_mfma_f32_16x16x32_bf16 v[86:89], v[150:153], v[182:185], v[86:89]
	v_mfma_f32_16x16x32_bf16 v[82:85], v[158:161], v[182:185], v[82:85]
	v_mfma_f32_16x16x32_bf16 v[70:73], v[150:153], v[210:213], v[70:73]
	v_mfma_f32_16x16x32_bf16 v[66:69], v[158:161], v[210:213], v[66:69]
	s_setprio 0
	s_barrier
; #define PG8_STAGE(bufoff, gbase, voff) do { _Pragma("unroll") for (int _i = 0; _i < 2; ++_i) \
;         __builtin_amdgcn_global_load_lds((const unsigned*)((const char*)(gbase) + (voff)[_i]), (PG8_LAS unsigned*)(lds + (bufoff) + ldsw + _i * 8192), 16, 0, 0); } while (0)
; #define PG8_LDA(dst, b, h) do { _Pragma("unroll") for (int m = 0; m < 4; ++m) _Pragma("unroll") for (int k = 0; k < 2; ++k) dst[m][k] = *(const PG8_LAS bf16x8*)(lds + PG8_SA(b, h) + aoff + m * 2048 + k * 1024); } while (0)
; #define PG8_MMA(ai, bj, At, Bt) do { __builtin_amdgcn_s_setprio(1); _Pragma("unroll") for (int k = 0; k < 2; ++k) _Pragma("unroll") for (int m = 0; m < 4; ++m) _Pragma("unroll") for (int n = 0; n < 2; ++n) \
;         acc[ai][bj][m][n] = __builtin_amdgcn_mfma_f32_16x16x32_bf16(Bt[n][k], At[m][k], acc[ai][bj][m][n], 0, 0, 0); __builtin_amdgcn_s_setprio(0); } while (0)
; #define PG8_WAIT_V(n) asm volatile("s_waitcnt vmcnt(" #n ")" ::: "memory")
; #define PG8_WAIT_L(n) asm volatile("s_waitcnt lgkmcnt(" #n ")" ::: "memory")
; #define PG8_BAR __builtin_amdgcn_s_barrier()
; #define PG8_SCHED __builtin_amdgcn_sched_barrier(0)
; template <class Epi, class Sched, bool ALIGN_EPI = false, bool SP2 = false>
; __device__ __forceinline__ void gemm_phase(PG8_LAS unsigned char* lds, const Gemm g, const Sched& S, const Epi& E, int tid_in) {
;     ...
;             PG8_LDA(At, 1, 1); PG8_STAGE(PG8_SB(1, 0), b3, voffB); PG8_STAGE(PG8_SB(1, 1), b3 + hstep, voffB); PG8_STAGE(PG8_SA(1, 0), a3, voffA);
;             PG8_WAIT_V(8); PG8_WAIT_L(0); PG8_BAR; PG8_MMA(1, 0, At, B0); PG8_MMA(1, 1, At, B1); PG8_BAR; PG8_SCHED;
	s_add_i32 s62, s33, s75
	v_lshl_add_u64 v[216:217], v[216:217], 0, s[26:27]
	s_mov_b32 m0, s62
	ds_read_b128 v[162:165], v215 offset:49152
	ds_read_b128 v[166:169], v215 offset:50176
	ds_read_b128 v[170:173], v215 offset:51200
	ds_read_b128 v[174:177], v215 offset:52224
	ds_read_b128 v[178:181], v215 offset:53248
	ds_read_b128 v[182:185], v215 offset:54272
	ds_read_b128 v[206:209], v215 offset:55296
	ds_read_b128 v[210:213], v215 offset:56320
	global_load_lds_dwordx4 v[216:217], off
	s_add_i32 m0, s62, 0x2000
	s_add_u32 s60, s60, 0x40080
	v_lshl_add_u64 v[216:217], v[218:219], 0, s[26:27]
	s_addc_u32 s61, s61, 0
	s_add_i32 s62, s74, s75
	global_load_lds_dwordx4 v[216:217], off
	v_lshl_add_u64 v[216:217], s[60:61], 0, v[0:1]
	s_mov_b32 m0, s62
	s_nop 0
	global_load_lds_dwordx4 v[216:217], off
	v_lshl_add_u64 v[216:217], s[60:61], 0, v[196:197]
	s_add_i32 m0, s62, 0x2000
	s_nop 0
	global_load_lds_dwordx4 v[216:217], off
	v_lshl_add_u64 v[216:217], v[220:221], 0, s[26:27]
	s_mov_b32 m0, s38
	s_nop 0
	global_load_lds_dwordx4 v[216:217], off
	v_lshl_add_u64 v[216:217], v[222:223], 0, s[26:27]
	s_mov_b32 m0, s39
	s_nop 0
	global_load_lds_dwordx4 v[216:217], off
	s_waitcnt vmcnt(8)
	s_waitcnt lgkmcnt(0)
	s_barrier
	s_setprio 1
	s_waitcnt lgkmcnt(0)
	v_mfma_f32_16x16x32_bf16 v[62:65], v[130:133], v[162:165], v[62:65]
	v_mfma_f32_16x16x32_bf16 v[58:61], v[138:141], v[162:165], v[58:61]
	v_mfma_f32_16x16x32_bf16 v[46:49], v[130:133], v[170:173], v[46:49]
	v_mfma_f32_16x16x32_bf16 v[42:45], v[138:141], v[170:173], v[42:45]
	v_mfma_f32_16x16x32_bf16 v[30:33], v[130:133], v[178:181], v[30:33]
	v_mfma_f32_16x16x32_bf16 v[26:29], v[138:141], v[178:181], v[26:29]
	v_mfma_f32_16x16x32_bf16 v[14:17], v[130:133], v[206:209], v[14:17]
	v_mfma_f32_16x16x32_bf16 v[10:13], v[138:141], v[206:209], v[10:13]
	v_mfma_f32_16x16x32_bf16 v[62:65], v[134:137], v[166:169], v[62:65]
	v_mfma_f32_16x16x32_bf16 v[58:61], v[142:145], v[166:169], v[58:61]
	v_mfma_f32_16x16x32_bf16 v[46:49], v[134:137], v[174:177], v[46:49]
	v_mfma_f32_16x16x32_bf16 v[42:45], v[142:145], v[174:177], v[42:45]
	v_mfma_f32_16x16x32_bf16 v[30:33], v[134:137], v[182:185], v[30:33]
	v_mfma_f32_16x16x32_bf16 v[26:29], v[142:145], v[182:185], v[26:29]
	v_mfma_f32_16x16x32_bf16 v[14:17], v[134:137], v[210:213], v[14:17]
	v_mfma_f32_16x16x32_bf16 v[10:13], v[142:145], v[210:213], v[10:13]
	s_setprio 0
	s_setprio 1
	v_mfma_f32_16x16x32_bf16 v[54:57], v[146:149], v[162:165], v[54:57]
	v_mfma_f32_16x16x32_bf16 v[50:53], v[154:157], v[162:165], v[50:53]
	v_mfma_f32_16x16x32_bf16 v[38:41], v[146:149], v[170:173], v[38:41]
	v_mfma_f32_16x16x32_bf16 v[34:37], v[154:157], v[170:173], v[34:37]
	v_mfma_f32_16x16x32_bf16 v[22:25], v[146:149], v[178:181], v[22:25]
	v_mfma_f32_16x16x32_bf16 v[18:21], v[154:157], v[178:181], v[18:21]
	v_mfma_f32_16x16x32_bf16 v[6:9], v[146:149], v[206:209], v[6:9]
	v_mfma_f32_16x16x32_bf16 v[2:5], v[154:157], v[206:209], v[2:5]
	v_mfma_f32_16x16x32_bf16 v[54:57], v[150:153], v[166:169], v[54:57]
	v_mfma_f32_16x16x32_bf16 v[50:53], v[158:161], v[166:169], v[50:53]
	v_mfma_f32_16x16x32_bf16 v[38:41], v[150:153], v[174:177], v[38:41]
	v_mfma_f32_16x16x32_bf16 v[34:37], v[158:161], v[174:177], v[34:37]
	v_mfma_f32_16x16x32_bf16 v[22:25], v[150:153], v[182:185], v[22:25]
	v_mfma_f32_16x16x32_bf16 v[18:21], v[158:161], v[182:185], v[18:21]
	v_mfma_f32_16x16x32_bf16 v[6:9], v[150:153], v[210:213], v[6:9]
	v_mfma_f32_16x16x32_bf16 v[2:5], v[158:161], v[210:213], v[2:5]
	s_setprio 0
	s_barrier
	s_add_i32 vcc_hi, vcc_hi, 2
	s_add_u32 s58, s58, 0x100
	s_addc_u32 s59, s59, 0
	s_add_u32 s83, s83, 0x100
	s_addc_u32 vcc_lo, vcc_lo, 0
	s_cmp_gt_u32 vcc_hi, 13

;     __device__ __forceinline__ bool next(int i, Unit& u) const { if (i >= n) return false; int o = own; asm volatile("" : "+s"(o)); u.pm = swap ? i : o; u.pn = swap ? o : i; u.idx = i; return true; }
; #define PG8_STAGE(bufoff, gbase, voff) do { _Pragma("unroll") for (int _i = 0; _i < 2; ++_i) \
;         __builtin_amdgcn_global_load_lds((const unsigned*)((const char*)(gbase) + (voff)[_i]), (PG8_LAS unsigned*)(lds + (bufoff) + ldsw + _i * 8192), 16, 0, 0); } while (0)
; #define PG8_LDA(dst, b, h) do { _Pragma("unroll") for (int m = 0; m < 4; ++m) _Pragma("unroll") for (int k = 0; k < 2; ++k) dst[m][k] = *(const PG8_LAS bf16x8*)(lds + PG8_SA(b, h) + aoff + m * 2048 + k * 1024); } while (0)
; template <class Epi, class Sched, bool ALIGN_EPI = false, bool SP2 = false>
; __device__ __forceinline__ void gemm_phase(PG8_LAS unsigned char* lds, const Gemm g, const Sched& S, const Epi& E, int tid_in) {
;     ...
;         const bool has_next = S.next(ui + 1, nxt);
;         const char* nA = has_next ? (const char*)g.A + (size_t)nxt.pm * tstep : cA; const char* nB = has_next ? (const char*)g.Bt + (size_t)nxt.pn * tstep : cB;
;         for (int t = 0; t < nt; t += 2) {
;             const bool last = (t == nt - 2);
;             const char* a1 = cA + (size_t)(t + 1) * kstep;
;             const char* a2 = last ? nA : cA + (size_t)(t + 2) * kstep; const char* b2 = last ? nB : cB + (size_t)(t + 2) * kstep;
;             const char* a3 = a2 + kstep; const char* b3 = b2 + kstep;
;             if (last && has_next) S.a_ready(nxt);
;             if constexpr (SP2) {
;             PG8_LDB(B0, 0, 0); PG8_LDB(B1, 0, 1); PG8_SCHED; PG8_LDA(At, 0, 0); PG8_STAGE(PG8_SA(1, 1), a1 + hstep, voffA);
;             PG8_WAIT_V(8); PG8_WAIT_L(0); PG8_BAR; PG8_MMA(0, 0, At, B0); PG8_MMA(0, 1, At, B1); PG8_BAR; PG8_SCHED;
;             PG8_LDA(At, 0, 1); PG8_STAGE(PG8_SB(0, 0), b2, voffB); PG8_STAGE(PG8_SB(0, 1), b2 + hstep, voffB); PG8_STAGE(PG8_SA(0, 0), a2, voffA);
;             PG8_WAIT_V(8); PG8_WAIT_L(0); PG8_BAR; PG8_MMA(1, 0, At, B0); PG8_MMA(1, 1, At, B1); PG8_BAR; PG8_SCHED;
;     ...
; #pragma unroll
;         for (int a = 0; a < 2; ++a)
; #pragma unroll
;             for (int b = 0; b < 2; ++b)
; #pragma unroll
;                 for (int m = 0; m < 4; ++m)
; #pragma unroll
;                     for (int n = 0; n < 2; ++n) acc[a][b][m][n] = (f32x4){0.f, 0.f, 0.f, 0.f};
.LBB0_491:
	s_ashr_i32 s43, s42, 31
	s_lshl_b64 s[48:49], s[42:43], 19
	s_add_u32 s48, s38, s48
	s_addc_u32 s49, s39, s49
	s_and_b64 s[50:51], s[46:47], exec
	s_cselect_b32 s43, s49, s53
	s_cselect_b32 s78, s48, s52
	s_ashr_i32 s45, s44, 31
	s_lshl_b64 s[50:51], s[44:45], 19
	s_add_u32 s50, s36, s50
	s_addc_u32 s51, s37, s51
	s_and_b64 s[56:57], s[46:47], exec
	s_cselect_b32 s45, s51, s55
	s_cselect_b32 s79, s50, s54
	s_add_u32 s52, s52, 0x40080
	s_addc_u32 s53, s53, 0
	s_add_u32 s80, s54, 0x100
	s_addc_u32 s81, s55, 0
	s_mov_b32 s82, -2
	v_add_u32_e32 v156, s84, v146
	v_add_u32_e32 v172, s85, v146
	ds_read_b128 v[140:143], v156
	ds_read_b128 v[148:151], v156 offset:1024
	ds_read_b128 v[152:155], v156 offset:2048
	ds_read_b128 v[156:159], v156 offset:3072
	ds_read_b128 v[160:163], v172
	ds_read_b128 v[164:167], v172 offset:1024
	ds_read_b128 v[168:171], v172 offset:2048
	ds_read_b128 v[172:175], v172 offset:3072
	s_add_u32 s54, s52, 0xfffc0080
	s_addc_u32 s55, s53, -1
	s_cmp_eq_u32 s82, 12
	s_cselect_b32 s57, s43, s55
	s_cselect_b32 s56, s78, s54
	s_cselect_b32 s55, s45, s81
	s_cselect_b32 s54, s79, s80
	v_lshl_add_u64 v[184:185], s[52:53], 0, v[136:137]
	s_add_i32 m0, s59, 0xc000
	ds_read_b128 v[176:179], v147
	ds_read_b128 v[180:183], v147 offset:1024
	ds_read_b128 v[196:199], v147 offset:2048
	ds_read_b128 v[200:203], v147 offset:3072
	ds_read_b128 v[204:207], v147 offset:4096
	ds_read_b128 v[208:211], v147 offset:5120
	ds_read_b128 v[212:215], v147 offset:6144
	ds_read_b128 v[216:219], v147 offset:7168
	global_load_lds_dwordx4 v[184:185], off
	v_lshl_add_u64 v[184:185], s[52:53], 0, v[138:139]
	s_add_i32 m0, s59, 0xe000
	s_nop 0
	global_load_lds_dwordx4 v[184:185], off
	s_waitcnt vmcnt(8)
	s_waitcnt lgkmcnt(0)
	s_barrier
	s_setprio 1
	s_waitcnt lgkmcnt(0)
	v_mfma_f32_16x16x32_bf16 v[126:129], v[140:143], v[176:179], 0
	v_mfma_f32_16x16x32_bf16 v[122:125], v[152:155], v[176:179], 0
	v_mfma_f32_16x16x32_bf16 v[110:113], v[140:143], v[196:199], 0
	v_mfma_f32_16x16x32_bf16 v[106:109], v[152:155], v[196:199], 0
	v_mfma_f32_16x16x32_bf16 v[94:97], v[140:143], v[204:207], 0
	v_mfma_f32_16x16x32_bf16 v[90:93], v[152:155], v[204:207], 0
	v_mfma_f32_16x16x32_bf16 v[78:81], v[140:143], v[212:215], 0
	v_mfma_f32_16x16x32_bf16 v[74:77], v[152:155], v[212:215], 0
	v_mfma_f32_16x16x32_bf16 v[126:129], v[148:151], v[180:183], v[126:129]
	v_mfma_f32_16x16x32_bf16 v[122:125], v[156:159], v[180:183], v[122:125]
	v_mfma_f32_16x16x32_bf16 v[110:113], v[148:151], v[200:203], v[110:113]
	v_mfma_f32_16x16x32_bf16 v[106:109], v[156:159], v[200:203], v[106:109]
	v_mfma_f32_16x16x32_bf16 v[94:97], v[148:151], v[208:211], v[94:97]
	v_mfma_f32_16x16x32_bf16 v[90:93], v[156:159], v[208:211], v[90:93]
	v_mfma_f32_16x16x32_bf16 v[78:81], v[148:151], v[216:219], v[78:81]
	v_mfma_f32_16x16x32_bf16 v[74:77], v[156:159], v[216:219], v[74:77]
	s_setprio 0
	s_setprio 1
	v_mfma_f32_16x16x32_bf16 v[118:121], v[160:163], v[176:179], 0
	v_mfma_f32_16x16x32_bf16 v[114:117], v[168:171], v[176:179], 0
	v_mfma_f32_16x16x32_bf16 v[102:105], v[160:163], v[196:199], 0
	v_mfma_f32_16x16x32_bf16 v[98:101], v[168:171], v[196:199], 0
	v_mfma_f32_16x16x32_bf16 v[86:89], v[160:163], v[204:207], 0
	v_mfma_f32_16x16x32_bf16 v[82:85], v[168:171], v[204:207], 0
	v_mfma_f32_16x16x32_bf16 v[70:73], v[160:163], v[212:215], 0
	v_mfma_f32_16x16x32_bf16 v[66:69], v[168:171], v[212:215], 0
	v_mfma_f32_16x16x32_bf16 v[118:121], v[164:167], v[180:183], v[118:121]
	v_mfma_f32_16x16x32_bf16 v[114:117], v[172:175], v[180:183], v[114:117]
	v_mfma_f32_16x16x32_bf16 v[102:105], v[164:167], v[200:203], v[102:105]
	v_mfma_f32_16x16x32_bf16 v[98:101], v[172:175], v[200:203], v[98:101]
	v_mfma_f32_16x16x32_bf16 v[86:89], v[164:167], v[208:211], v[86:89]
	v_mfma_f32_16x16x32_bf16 v[82:85], v[172:175], v[208:211], v[82:85]
	v_mfma_f32_16x16x32_bf16 v[70:73], v[164:167], v[216:219], v[70:73]
	v_mfma_f32_16x16x32_bf16 v[66:69], v[172:175], v[216:219], v[66:69]
	s_setprio 0
	s_barrier
	s_add_i32 s83, s84, s58
	v_lshl_add_u64 v[184:185], s[54:55], 0, v[0:1]
	s_mov_b32 m0, s83
	ds_read_b128 v[176:179], v147 offset:16384
	ds_read_b128 v[180:183], v147 offset:17408
	ds_read_b128 v[196:199], v147 offset:18432
	ds_read_b128 v[200:203], v147 offset:19456
	ds_read_b128 v[204:207], v147 offset:20480
	ds_read_b128 v[208:211], v147 offset:21504
	ds_read_b128 v[212:215], v147 offset:22528
	ds_read_b128 v[216:219], v147 offset:23552
	global_load_lds_dwordx4 v[184:185], off
	s_add_i32 m0, s83, 0x2000
	s_add_u32 s86, s54, 0x40000
	v_lshl_add_u64 v[220:221], s[54:55], 0, v[130:131]
	s_addc_u32 s87, s55, 0
	s_add_i32 s83, s85, s58
	global_load_lds_dwordx4 v[220:221], off
	v_lshl_add_u64 v[222:223], s[86:87], 0, v[0:1]
	s_mov_b32 m0, s83
	v_lshl_add_u64 v[224:225], s[56:57], 0, v[132:133]
	global_load_lds_dwordx4 v[222:223], off
	v_lshl_add_u64 v[222:223], s[86:87], 0, v[130:131]
	s_add_i32 m0, s83, 0x2000
	s_nop 0
	global_load_lds_dwordx4 v[222:223], off
	v_lshl_add_u64 v[222:223], s[56:57], 0, v[134:135]
	s_mov_b32 m0, s59
	s_nop 0
	global_load_lds_dwordx4 v[222:223], off
	s_mov_b32 m0, s60
	s_nop 0
	global_load_lds_dwordx4 v[224:225], off
	s_waitcnt vmcnt(8)
	s_waitcnt lgkmcnt(0)
	s_barrier
; #define PG8_STAGE(bufoff, gbase, voff) do { _Pragma("unroll") for (int _i = 0; _i < 2; ++_i) \
;         __builtin_amdgcn_global_load_lds((const unsigned*)((const char*)(gbase) + (voff)[_i]), (PG8_LAS unsigned*)(lds + (bufoff) + ldsw + _i * 8192), 16, 0, 0); } while (0)
; #define PG8_LDA(dst, b, h) do { _Pragma("unroll") for (int m = 0; m < 4; ++m) _Pragma("unroll") for (int k = 0; k < 2; ++k) dst[m][k] = *(const PG8_LAS bf16x8*)(lds + PG8_SA(b, h) + aoff + m * 2048 + k * 1024); } while (0)
; #define PG8_LDB(dst, b, h) do { _Pragma("unroll") for (int n = 0; n < 2; ++n) _Pragma("unroll") for (int k = 0; k < 2; ++k) dst[n][k] = *(const PG8_LAS bf16x8*)(lds + PG8_SB(b, h) + boff + n * 2048 + k * 1024); } while (0)
; #define PG8_MMA(ai, bj, At, Bt) do { __builtin_amdgcn_s_setprio(1); _Pragma("unroll") for (int k = 0; k < 2; ++k) _Pragma("unroll") for (int m = 0; m < 4; ++m) _Pragma("unroll") for (int n = 0; n < 2; ++n) \
;         acc[ai][bj][m][n] = __builtin_amdgcn_mfma_f32_16x16x32_bf16(Bt[n][k], At[m][k], acc[ai][bj][m][n], 0, 0, 0); __builtin_amdgcn_s_setprio(0); } while (0)
; #define PG8_WAIT_V(n) asm volatile("s_waitcnt vmcnt(" #n ")" ::: "memory")
; #define PG8_WAIT_L(n) asm volatile("s_waitcnt lgkmcnt(" #n ")" ::: "memory")
; #define PG8_BAR __builtin_amdgcn_s_barrier()
; #define PG8_SCHED __builtin_amdgcn_sched_barrier(0)
; template <class Epi, class Sched, bool ALIGN_EPI = false, bool SP2 = false>
; __device__ __forceinline__ void gemm_phase(PG8_LAS unsigned char* lds, const Gemm g, const Sched& S, const Epi& E, int tid_in) {
;     ...
;             PG8_WAIT_V(8); PG8_WAIT_L(0); PG8_BAR; PG8_MMA(1, 0, At, B0); PG8_MMA(1, 1, At, B1); PG8_BAR; PG8_SCHED;
;             PG8_LDB(B0, 1, 0); PG8_LDB(B1, 1, 1); PG8_SCHED; PG8_LDA(At, 1, 0); PG8_STAGE(PG8_SA(0, 1), a2 + hstep, voffA);
;             PG8_WAIT_V(8); PG8_WAIT_L(0); PG8_BAR; PG8_MMA(0, 0, At, B0); PG8_MMA(0, 1, At, B1); PG8_BAR; PG8_SCHED;
	s_setprio 1
	s_waitcnt lgkmcnt(0)
	v_mfma_f32_16x16x32_bf16 v[62:65], v[140:143], v[176:179], 0
	v_mfma_f32_16x16x32_bf16 v[58:61], v[152:155], v[176:179], 0
	v_mfma_f32_16x16x32_bf16 v[46:49], v[140:143], v[196:199], 0
	v_mfma_f32_16x16x32_bf16 v[42:45], v[152:155], v[196:199], 0
	v_mfma_f32_16x16x32_bf16 v[30:33], v[140:143], v[204:207], 0
	v_mfma_f32_16x16x32_bf16 v[26:29], v[152:155], v[204:207], 0
	v_mfma_f32_16x16x32_bf16 v[14:17], v[140:143], v[212:215], 0
	v_mfma_f32_16x16x32_bf16 v[10:13], v[152:155], v[212:215], 0
	v_mfma_f32_16x16x32_bf16 v[62:65], v[148:151], v[180:183], v[62:65]
	v_mfma_f32_16x16x32_bf16 v[58:61], v[156:159], v[180:183], v[58:61]
	v_mfma_f32_16x16x32_bf16 v[46:49], v[148:151], v[200:203], v[46:49]
	v_mfma_f32_16x16x32_bf16 v[42:45], v[156:159], v[200:203], v[42:45]
	v_mfma_f32_16x16x32_bf16 v[30:33], v[148:151], v[208:211], v[30:33]
	v_mfma_f32_16x16x32_bf16 v[26:29], v[156:159], v[208:211], v[26:29]
	v_mfma_f32_16x16x32_bf16 v[14:17], v[148:151], v[216:219], v[14:17]
	v_mfma_f32_16x16x32_bf16 v[10:13], v[156:159], v[216:219], v[10:13]
	s_setprio 0
	s_setprio 1
	v_mfma_f32_16x16x32_bf16 v[54:57], v[160:163], v[176:179], 0
	v_mfma_f32_16x16x32_bf16 v[50:53], v[168:171], v[176:179], 0
	v_mfma_f32_16x16x32_bf16 v[38:41], v[160:163], v[196:199], 0
	v_mfma_f32_16x16x32_bf16 v[34:37], v[168:171], v[196:199], 0
	v_mfma_f32_16x16x32_bf16 v[22:25], v[160:163], v[204:207], 0
	v_mfma_f32_16x16x32_bf16 v[18:21], v[168:171], v[204:207], 0
	v_mfma_f32_16x16x32_bf16 v[6:9], v[160:163], v[212:215], 0
	v_mfma_f32_16x16x32_bf16 v[2:5], v[168:171], v[212:215], 0
	v_mfma_f32_16x16x32_bf16 v[54:57], v[164:167], v[180:183], v[54:57]
	v_mfma_f32_16x16x32_bf16 v[50:53], v[172:175], v[180:183], v[50:53]
	v_mfma_f32_16x16x32_bf16 v[38:41], v[164:167], v[200:203], v[38:41]
	v_mfma_f32_16x16x32_bf16 v[34:37], v[172:175], v[200:203], v[34:37]
	v_mfma_f32_16x16x32_bf16 v[22:25], v[164:167], v[208:211], v[22:25]
	v_mfma_f32_16x16x32_bf16 v[18:21], v[172:175], v[208:211], v[18:21]
	v_mfma_f32_16x16x32_bf16 v[6:9], v[164:167], v[216:219], v[6:9]
	v_mfma_f32_16x16x32_bf16 v[2:5], v[172:175], v[216:219], v[2:5]
	s_setprio 0
	s_barrier
	v_add_u32_e32 v156, s33, v146
	v_add_u32_e32 v172, s74, v146
	ds_read_b128 v[140:143], v156
	ds_read_b128 v[148:151], v156 offset:1024
	ds_read_b128 v[152:155], v156 offset:2048
	ds_read_b128 v[156:159], v156 offset:3072
	ds_read_b128 v[160:163], v172
	ds_read_b128 v[164:167], v172 offset:1024
	ds_read_b128 v[168:171], v172 offset:2048
	ds_read_b128 v[172:175], v172 offset:3072
	s_add_u32 s56, s56, 0x40000
	s_addc_u32 s57, s57, 0
	s_mov_b32 m0, s61
	v_lshl_add_u64 v[226:227], s[56:57], 0, v[134:135]
	ds_read_b128 v[176:179], v147 offset:32768
	ds_read_b128 v[180:183], v147 offset:33792
	ds_read_b128 v[196:199], v147 offset:34816
	ds_read_b128 v[200:203], v147 offset:35840
	ds_read_b128 v[204:207], v147 offset:36864
	ds_read_b128 v[208:211], v147 offset:37888
	ds_read_b128 v[212:215], v147 offset:38912
	ds_read_b128 v[216:219], v147 offset:39936
	global_load_lds_dwordx4 v[226:227], off
	v_lshl_add_u64 v[226:227], s[56:57], 0, v[132:133]
	s_mov_b32 m0, s62
	s_nop 0
	global_load_lds_dwordx4 v[226:227], off
	s_waitcnt vmcnt(8)
	s_waitcnt lgkmcnt(0)
	s_barrier
	s_setprio 1
	s_waitcnt lgkmcnt(0)
	v_mfma_f32_16x16x32_bf16 v[126:129], v[140:143], v[176:179], v[126:129]
	v_mfma_f32_16x16x32_bf16 v[122:125], v[152:155], v[176:179], v[122:125]
	v_mfma_f32_16x16x32_bf16 v[110:113], v[140:143], v[196:199], v[110:113]
	v_mfma_f32_16x16x32_bf16 v[106:109], v[152:155], v[196:199], v[106:109]
	v_mfma_f32_16x16x32_bf16 v[94:97], v[140:143], v[204:207], v[94:97]
	v_mfma_f32_16x16x32_bf16 v[90:93], v[152:155], v[204:207], v[90:93]
	v_mfma_f32_16x16x32_bf16 v[78:81], v[140:143], v[212:215], v[78:81]
	v_mfma_f32_16x16x32_bf16 v[74:77], v[152:155], v[212:215], v[74:77]
	v_mfma_f32_16x16x32_bf16 v[126:129], v[148:151], v[180:183], v[126:129]
	v_mfma_f32_16x16x32_bf16 v[122:125], v[156:159], v[180:183], v[122:125]
	v_mfma_f32_16x16x32_bf16 v[110:113], v[148:151], v[200:203], v[110:113]
	v_mfma_f32_16x16x32_bf16 v[106:109], v[156:159], v[200:203], v[106:109]
	v_mfma_f32_16x16x32_bf16 v[94:97], v[148:151], v[208:211], v[94:97]
	v_mfma_f32_16x16x32_bf16 v[90:93], v[156:159], v[208:211], v[90:93]
	v_mfma_f32_16x16x32_bf16 v[78:81], v[148:151], v[216:219], v[78:81]
	v_mfma_f32_16x16x32_bf16 v[74:77], v[156:159], v[216:219], v[74:77]
	s_setprio 0
	s_setprio 1
	v_mfma_f32_16x16x32_bf16 v[118:121], v[160:163], v[176:179], v[118:121]
	v_mfma_f32_16x16x32_bf16 v[114:117], v[168:171], v[176:179], v[114:117]
	v_mfma_f32_16x16x32_bf16 v[102:105], v[160:163], v[196:199], v[102:105]
	v_mfma_f32_16x16x32_bf16 v[98:101], v[168:171], v[196:199], v[98:101]
	v_mfma_f32_16x16x32_bf16 v[86:89], v[160:163], v[204:207], v[86:89]
	v_mfma_f32_16x16x32_bf16 v[82:85], v[168:171], v[204:207], v[82:85]
	v_mfma_f32_16x16x32_bf16 v[70:73], v[160:163], v[212:215], v[70:73]
	v_mfma_f32_16x16x32_bf16 v[66:69], v[168:171], v[212:215], v[66:69]
	v_mfma_f32_16x16x32_bf16 v[118:121], v[164:167], v[180:183], v[118:121]
	v_mfma_f32_16x16x32_bf16 v[114:117], v[172:175], v[180:183], v[114:117]
	v_mfma_f32_16x16x32_bf16 v[102:105], v[164:167], v[200:203], v[102:105]
	v_mfma_f32_16x16x32_bf16 v[98:101], v[172:175], v[200:203], v[98:101]
	v_mfma_f32_16x16x32_bf16 v[86:89], v[164:167], v[208:211], v[86:89]
	v_mfma_f32_16x16x32_bf16 v[82:85], v[172:175], v[208:211], v[82:85]
	v_mfma_f32_16x16x32_bf16 v[70:73], v[164:167], v[216:219], v[70:73]
	v_mfma_f32_16x16x32_bf16 v[66:69], v[172:175], v[216:219], v[66:69]
	s_setprio 0
	s_barrier
; #define PG8_STAGE(bufoff, gbase, voff) do { _Pragma("unroll") for (int _i = 0; _i < 2; ++_i) \
;         __builtin_amdgcn_global_load_lds((const unsigned*)((const char*)(gbase) + (voff)[_i]), (PG8_LAS unsigned*)(lds + (bufoff) + ldsw + _i * 8192), 16, 0, 0); } while (0)
; #define PG8_LDA(dst, b, h) do { _Pragma("unroll") for (int m = 0; m < 4; ++m) _Pragma("unroll") for (int k = 0; k < 2; ++k) dst[m][k] = *(const PG8_LAS bf16x8*)(lds + PG8_SA(b, h) + aoff + m * 2048 + k * 1024); } while (0)
; #define PG8_MMA(ai, bj, At, Bt) do { __builtin_amdgcn_s_setprio(1); _Pragma("unroll") for (int k = 0; k < 2; ++k) _Pragma("unroll") for (int m = 0; m < 4; ++m) _Pragma("unroll") for (int n = 0; n < 2; ++n) \
;         acc[ai][bj][m][n] = __builtin_amdgcn_mfma_f32_16x16x32_bf16(Bt[n][k], At[m][k], acc[ai][bj][m][n], 0, 0, 0); __builtin_amdgcn_s_setprio(0); } while (0)
; #define PG8_WAIT_V(n) asm volatile("s_waitcnt vmcnt(" #n ")" ::: "memory")
; #define PG8_WAIT_L(n) asm volatile("s_waitcnt lgkmcnt(" #n ")" ::: "memory")
; #define PG8_BAR __builtin_amdgcn_s_barrier()
; #define PG8_SCHED __builtin_amdgcn_sched_barrier(0)
; template <class Epi, class Sched, bool ALIGN_EPI = false, bool SP2 = false>
; __device__ __forceinline__ void gemm_phase(PG8_LAS unsigned char* lds, const Gemm g, const Sched& S, const Epi& E, int tid_in) {
;     ...
;             PG8_LDA(At, 1, 1); PG8_STAGE(PG8_SB(1, 0), b3, voffB); PG8_STAGE(PG8_SB(1, 1), b3 + hstep, voffB); PG8_STAGE(PG8_SA(1, 0), a3, voffA);
;             PG8_WAIT_V(8); PG8_WAIT_L(0); PG8_BAR; PG8_MMA(1, 0, At, B0); PG8_MMA(1, 1, At, B1); PG8_BAR; PG8_SCHED;
	s_add_i32 s56, s33, s58
	v_lshl_add_u64 v[184:185], v[184:185], 0, s[26:27]
	s_mov_b32 m0, s56
	ds_read_b128 v[176:179], v147 offset:49152
	ds_read_b128 v[180:183], v147 offset:50176
	ds_read_b128 v[196:199], v147 offset:51200
	ds_read_b128 v[200:203], v147 offset:52224
	ds_read_b128 v[204:207], v147 offset:53248
	ds_read_b128 v[208:211], v147 offset:54272
	ds_read_b128 v[212:215], v147 offset:55296
	ds_read_b128 v[216:219], v147 offset:56320
	global_load_lds_dwordx4 v[184:185], off
	s_add_i32 m0, s56, 0x2000
	s_add_u32 s54, s54, 0x40080
	v_lshl_add_u64 v[184:185], v[220:221], 0, s[26:27]
	s_addc_u32 s55, s55, 0
	s_add_i32 s56, s74, s58
	global_load_lds_dwordx4 v[184:185], off
	v_lshl_add_u64 v[184:185], s[54:55], 0, v[0:1]
	s_mov_b32 m0, s56
	s_nop 0
	global_load_lds_dwordx4 v[184:185], off
	v_lshl_add_u64 v[184:185], s[54:55], 0, v[130:131]
	s_add_i32 m0, s56, 0x2000
	s_nop 0
	global_load_lds_dwordx4 v[184:185], off
	v_lshl_add_u64 v[184:185], v[222:223], 0, s[26:27]
	s_mov_b32 m0, s65
	s_nop 0
	global_load_lds_dwordx4 v[184:185], off
	v_lshl_add_u64 v[184:185], v[224:225], 0, s[26:27]
	s_mov_b32 m0, s68
	s_nop 0
	global_load_lds_dwordx4 v[184:185], off
	s_waitcnt vmcnt(8)
	s_waitcnt lgkmcnt(0)
	s_barrier
	s_setprio 1
	s_waitcnt lgkmcnt(0)
	v_mfma_f32_16x16x32_bf16 v[62:65], v[140:143], v[176:179], v[62:65]
	v_mfma_f32_16x16x32_bf16 v[58:61], v[152:155], v[176:179], v[58:61]
	v_mfma_f32_16x16x32_bf16 v[46:49], v[140:143], v[196:199], v[46:49]
	v_mfma_f32_16x16x32_bf16 v[42:45], v[152:155], v[196:199], v[42:45]
	v_mfma_f32_16x16x32_bf16 v[30:33], v[140:143], v[204:207], v[30:33]
	v_mfma_f32_16x16x32_bf16 v[26:29], v[152:155], v[204:207], v[26:29]
	v_mfma_f32_16x16x32_bf16 v[14:17], v[140:143], v[212:215], v[14:17]
	v_mfma_f32_16x16x32_bf16 v[10:13], v[152:155], v[212:215], v[10:13]
	v_mfma_f32_16x16x32_bf16 v[62:65], v[148:151], v[180:183], v[62:65]
	v_mfma_f32_16x16x32_bf16 v[58:61], v[156:159], v[180:183], v[58:61]
	v_mfma_f32_16x16x32_bf16 v[46:49], v[148:151], v[200:203], v[46:49]
	v_mfma_f32_16x16x32_bf16 v[42:45], v[156:159], v[200:203], v[42:45]
	v_mfma_f32_16x16x32_bf16 v[30:33], v[148:151], v[208:211], v[30:33]
	v_mfma_f32_16x16x32_bf16 v[26:29], v[156:159], v[208:211], v[26:29]
	v_mfma_f32_16x16x32_bf16 v[14:17], v[148:151], v[216:219], v[14:17]
	v_mfma_f32_16x16x32_bf16 v[10:13], v[156:159], v[216:219], v[10:13]
	s_setprio 0
	s_setprio 1
	v_mfma_f32_16x16x32_bf16 v[54:57], v[160:163], v[176:179], v[54:57]
	v_mfma_f32_16x16x32_bf16 v[50:53], v[168:171], v[176:179], v[50:53]
	v_mfma_f32_16x16x32_bf16 v[38:41], v[160:163], v[196:199], v[38:41]
	v_mfma_f32_16x16x32_bf16 v[34:37], v[168:171], v[196:199], v[34:37]
	v_mfma_f32_16x16x32_bf16 v[22:25], v[160:163], v[204:207], v[22:25]
	v_mfma_f32_16x16x32_bf16 v[18:21], v[168:171], v[204:207], v[18:21]
	v_mfma_f32_16x16x32_bf16 v[6:9], v[160:163], v[212:215], v[6:9]
	v_mfma_f32_16x16x32_bf16 v[2:5], v[168:171], v[212:215], v[2:5]
	v_mfma_f32_16x16x32_bf16 v[54:57], v[164:167], v[180:183], v[54:57]
	v_mfma_f32_16x16x32_bf16 v[50:53], v[172:175], v[180:183], v[50:53]
	v_mfma_f32_16x16x32_bf16 v[38:41], v[164:167], v[200:203], v[38:41]
	v_mfma_f32_16x16x32_bf16 v[34:37], v[172:175], v[200:203], v[34:37]
	v_mfma_f32_16x16x32_bf16 v[22:25], v[164:167], v[208:211], v[22:25]
	v_mfma_f32_16x16x32_bf16 v[18:21], v[172:175], v[208:211], v[18:21]
	v_mfma_f32_16x16x32_bf16 v[6:9], v[164:167], v[216:219], v[6:9]
	v_mfma_f32_16x16x32_bf16 v[2:5], v[172:175], v[216:219], v[2:5]
	s_setprio 0
	s_barrier
	s_add_i32 s82, s82, 2
	s_add_u32 s52, s52, 0x100
	s_addc_u32 s53, s53, 0
	s_add_u32 s80, s80, 0x100
	s_addc_u32 s81, s81, 0
	s_cmp_gt_u32 s82, 13

;     __device__ __forceinline__ bool next(int i, Unit& u) const { if (i >= n) return false; int o = own; asm volatile("" : "+s"(o)); u.pm = swap ? i : o; u.pn = swap ? o : i; u.idx = i; return true; }
; #define PG8_STAGE(bufoff, gbase, voff) do { _Pragma("unroll") for (int _i = 0; _i < 2; ++_i) \
;         __builtin_amdgcn_global_load_lds((const unsigned*)((const char*)(gbase) + (voff)[_i]), (PG8_LAS unsigned*)(lds + (bufoff) + ldsw + _i * 8192), 16, 0, 0); } while (0)
; #define PG8_LDA(dst, b, h) do { _Pragma("unroll") for (int m = 0; m < 4; ++m) _Pragma("unroll") for (int k = 0; k < 2; ++k) dst[m][k] = *(const PG8_LAS bf16x8*)(lds + PG8_SA(b, h) + aoff + m * 2048 + k * 1024); } while (0)
; template <class Epi, class Sched, bool ALIGN_EPI = false, bool SP2 = false>
; __device__ __forceinline__ void gemm_phase(PG8_LAS unsigned char* lds, const Gemm g, const Sched& S, const Epi& E, int tid_in) {
;     ...
;         const bool has_next = S.next(ui + 1, nxt);
;         const char* nA = has_next ? (const char*)g.A + (size_t)nxt.pm * tstep : cA; const char* nB = has_next ? (const char*)g.Bt + (size_t)nxt.pn * tstep : cB;
;         for (int t = 0; t < nt; t += 2) {
;             const bool last = (t == nt - 2);
;             const char* a1 = cA + (size_t)(t + 1) * kstep;
;             const char* a2 = last ? nA : cA + (size_t)(t + 2) * kstep; const char* b2 = last ? nB : cB + (size_t)(t + 2) * kstep;
;             const char* a3 = a2 + kstep; const char* b3 = b2 + kstep;
;             if (last && has_next) S.a_ready(nxt);
;             if constexpr (SP2) {
;             PG8_LDB(B0, 0, 0); PG8_LDB(B1, 0, 1); PG8_SCHED; PG8_LDA(At, 0, 0); PG8_STAGE(PG8_SA(1, 1), a1 + hstep, voffA);
;             PG8_WAIT_V(8); PG8_WAIT_L(0); PG8_BAR; PG8_MMA(0, 0, At, B0); PG8_MMA(0, 1, At, B1); PG8_BAR; PG8_SCHED;
;             PG8_LDA(At, 0, 1); PG8_STAGE(PG8_SB(0, 0), b2, voffB); PG8_STAGE(PG8_SB(0, 1), b2 + hstep, voffB); PG8_STAGE(PG8_SA(0, 0), a2, voffA);
;             PG8_WAIT_V(8); PG8_WAIT_L(0); PG8_BAR; PG8_MMA(1, 0, At, B0); PG8_MMA(1, 1, At, B1); PG8_BAR; PG8_SCHED;
;     ...
; #pragma unroll
;         for (int a = 0; a < 2; ++a)
; #pragma unroll
;             for (int b = 0; b < 2; ++b)
; #pragma unroll
;                 for (int m = 0; m < 4; ++m)
; #pragma unroll
;                     for (int n = 0; n < 2; ++n) acc[a][b][m][n] = (f32x4){0.f, 0.f, 0.f, 0.f};
.LBB0_566:
	s_ashr_i32 s43, s42, 31
	s_lshl_b64 s[46:47], s[42:43], 21
	s_add_u32 s46, s58, s46
	s_addc_u32 s47, s59, s47
	s_and_b64 s[48:49], s[40:41], exec
	s_cselect_b32 s43, s47, s51
	s_cselect_b32 s79, s46, s50
	s_ashr_i32 s45, s44, 31
	s_lshl_b64 s[48:49], s[44:45], 21
	s_add_u32 s48, s56, s48
	s_addc_u32 s49, s57, s49
	s_and_b64 s[54:55], s[40:41], exec
	s_cselect_b32 s45, s49, s53
	s_cselect_b32 s80, s48, s52
	s_add_u32 s50, s50, 0x100080
	s_addc_u32 s51, s51, 0
	s_add_u32 s81, s52, 0x100
	s_addc_u32 s82, s53, 0
	s_mov_b32 s83, -2
	s_waitcnt lgkmcnt(0)
	v_add_u32_e32 v134, s84, v210
	v_add_u32_e32 v158, s85, v210
	ds_read_b128 v[106:109], v134
	ds_read_b128 v[110:113], v134 offset:1024
	ds_read_b128 v[130:133], v134 offset:2048
	ds_read_b128 v[134:137], v134 offset:3072
	ds_read_b128 v[146:149], v158
	ds_read_b128 v[150:153], v158 offset:1024
	ds_read_b128 v[154:157], v158 offset:2048
	ds_read_b128 v[158:161], v158 offset:3072
	s_add_u32 s52, s50, 0xfff00080
	s_addc_u32 s53, s51, -1
	s_cmp_eq_u32 s83, 60
	s_cselect_b32 s55, s43, s53
	s_cselect_b32 s54, s79, s52
	s_cselect_b32 s53, s45, s82
	s_cselect_b32 s52, s80, s81
	v_lshl_add_u64 v[216:217], s[50:51], 0, v[202:203]
	s_add_i32 m0, s61, 0xc000
	ds_read_b128 v[162:165], v211
	ds_read_b128 v[166:169], v211 offset:1024
	ds_read_b128 v[170:173], v211 offset:2048
	ds_read_b128 v[174:177], v211 offset:3072
	ds_read_b128 v[178:181], v211 offset:4096
	ds_read_b128 v[182:185], v211 offset:5120
	ds_read_b128 v[206:209], v211 offset:6144
	ds_read_b128 v[212:215], v211 offset:7168
	global_load_lds_dwordx4 v[216:217], off
	v_lshl_add_u64 v[216:217], s[50:51], 0, v[204:205]
	s_add_i32 m0, s61, 0xe000
	s_nop 0
	global_load_lds_dwordx4 v[216:217], off
	s_waitcnt vmcnt(8)
	s_waitcnt lgkmcnt(0)
	s_barrier
	s_setprio 1
	s_waitcnt lgkmcnt(0)
	v_mfma_f32_16x16x32_bf16 v[142:145], v[106:109], v[162:165], 0
	v_mfma_f32_16x16x32_bf16 v[138:141], v[130:133], v[162:165], 0
	v_mfma_f32_16x16x32_bf16 v[118:121], v[106:109], v[170:173], 0
	v_mfma_f32_16x16x32_bf16 v[114:117], v[130:133], v[170:173], 0
	v_mfma_f32_16x16x32_bf16 v[94:97], v[106:109], v[178:181], 0
	v_mfma_f32_16x16x32_bf16 v[90:93], v[130:133], v[178:181], 0
	v_mfma_f32_16x16x32_bf16 v[78:81], v[106:109], v[206:209], 0
	v_mfma_f32_16x16x32_bf16 v[74:77], v[130:133], v[206:209], 0
	v_mfma_f32_16x16x32_bf16 v[142:145], v[110:113], v[166:169], v[142:145]
	v_mfma_f32_16x16x32_bf16 v[138:141], v[134:137], v[166:169], v[138:141]
	v_mfma_f32_16x16x32_bf16 v[118:121], v[110:113], v[174:177], v[118:121]
	v_mfma_f32_16x16x32_bf16 v[114:117], v[134:137], v[174:177], v[114:117]
	v_mfma_f32_16x16x32_bf16 v[94:97], v[110:113], v[182:185], v[94:97]
	v_mfma_f32_16x16x32_bf16 v[90:93], v[134:137], v[182:185], v[90:93]
	v_mfma_f32_16x16x32_bf16 v[78:81], v[110:113], v[212:215], v[78:81]
	v_mfma_f32_16x16x32_bf16 v[74:77], v[134:137], v[212:215], v[74:77]
	s_setprio 0
	s_setprio 1
	v_mfma_f32_16x16x32_bf16 v[126:129], v[146:149], v[162:165], 0
	v_mfma_f32_16x16x32_bf16 v[122:125], v[154:157], v[162:165], 0
	v_mfma_f32_16x16x32_bf16 v[102:105], v[146:149], v[170:173], 0
	v_mfma_f32_16x16x32_bf16 v[98:101], v[154:157], v[170:173], 0
	v_mfma_f32_16x16x32_bf16 v[86:89], v[146:149], v[178:181], 0
	v_mfma_f32_16x16x32_bf16 v[82:85], v[154:157], v[178:181], 0
	v_mfma_f32_16x16x32_bf16 v[70:73], v[146:149], v[206:209], 0
	v_mfma_f32_16x16x32_bf16 v[66:69], v[154:157], v[206:209], 0
	v_mfma_f32_16x16x32_bf16 v[126:129], v[150:153], v[166:169], v[126:129]
	v_mfma_f32_16x16x32_bf16 v[122:125], v[158:161], v[166:169], v[122:125]
	v_mfma_f32_16x16x32_bf16 v[102:105], v[150:153], v[174:177], v[102:105]
	v_mfma_f32_16x16x32_bf16 v[98:101], v[158:161], v[174:177], v[98:101]
	v_mfma_f32_16x16x32_bf16 v[86:89], v[150:153], v[182:185], v[86:89]
	v_mfma_f32_16x16x32_bf16 v[82:85], v[158:161], v[182:185], v[82:85]
	v_mfma_f32_16x16x32_bf16 v[70:73], v[150:153], v[212:215], v[70:73]
	v_mfma_f32_16x16x32_bf16 v[66:69], v[158:161], v[212:215], v[66:69]
	s_setprio 0
	s_barrier
	s_add_i32 s86, s84, s60
	v_lshl_add_u64 v[216:217], s[52:53], 0, v[0:1]
	s_mov_b32 m0, s86
	ds_read_b128 v[162:165], v211 offset:16384
	ds_read_b128 v[166:169], v211 offset:17408
	ds_read_b128 v[170:173], v211 offset:18432
	ds_read_b128 v[174:177], v211 offset:19456
	ds_read_b128 v[178:181], v211 offset:20480
	ds_read_b128 v[182:185], v211 offset:21504
	ds_read_b128 v[206:209], v211 offset:22528
	ds_read_b128 v[212:215], v211 offset:23552
	global_load_lds_dwordx4 v[216:217], off
	s_add_i32 m0, s86, 0x2000
	s_add_u32 s86, s52, 0x100000
	v_lshl_add_u64 v[218:219], s[52:53], 0, v[196:197]
	s_addc_u32 s87, s53, 0
	s_add_i32 s92, s85, s60
	global_load_lds_dwordx4 v[218:219], off
	v_lshl_add_u64 v[220:221], s[86:87], 0, v[0:1]
	s_mov_b32 m0, s92
	v_lshl_add_u64 v[222:223], s[54:55], 0, v[198:199]
	global_load_lds_dwordx4 v[220:221], off
	v_lshl_add_u64 v[220:221], s[86:87], 0, v[196:197]
	s_add_i32 m0, s92, 0x2000
	s_nop 0
	global_load_lds_dwordx4 v[220:221], off
	v_lshl_add_u64 v[220:221], s[54:55], 0, v[200:201]
	s_mov_b32 m0, s61
	s_nop 0
	global_load_lds_dwordx4 v[220:221], off
	s_mov_b32 m0, s62
	s_nop 0
	global_load_lds_dwordx4 v[222:223], off
	s_waitcnt vmcnt(8)
	s_waitcnt lgkmcnt(0)
	s_barrier
; #define PG8_STAGE(bufoff, gbase, voff) do { _Pragma("unroll") for (int _i = 0; _i < 2; ++_i) \
;         __builtin_amdgcn_global_load_lds((const unsigned*)((const char*)(gbase) + (voff)[_i]), (PG8_LAS unsigned*)(lds + (bufoff) + ldsw + _i * 8192), 16, 0, 0); } while (0)
; #define PG8_LDA(dst, b, h) do { _Pragma("unroll") for (int m = 0; m < 4; ++m) _Pragma("unroll") for (int k = 0; k < 2; ++k) dst[m][k] = *(const PG8_LAS bf16x8*)(lds + PG8_SA(b, h) + aoff + m * 2048 + k * 1024); } while (0)
; #define PG8_LDB(dst, b, h) do { _Pragma("unroll") for (int n = 0; n < 2; ++n) _Pragma("unroll") for (int k = 0; k < 2; ++k) dst[n][k] = *(const PG8_LAS bf16x8*)(lds + PG8_SB(b, h) + boff + n * 2048 + k * 1024); } while (0)
; #define PG8_MMA(ai, bj, At, Bt) do { __builtin_amdgcn_s_setprio(1); _Pragma("unroll") for (int k = 0; k < 2; ++k) _Pragma("unroll") for (int m = 0; m < 4; ++m) _Pragma("unroll") for (int n = 0; n < 2; ++n) \
;         acc[ai][bj][m][n] = __builtin_amdgcn_mfma_f32_16x16x32_bf16(Bt[n][k], At[m][k], acc[ai][bj][m][n], 0, 0, 0); __builtin_amdgcn_s_setprio(0); } while (0)
; #define PG8_WAIT_V(n) asm volatile("s_waitcnt vmcnt(" #n ")" ::: "memory")
; #define PG8_WAIT_L(n) asm volatile("s_waitcnt lgkmcnt(" #n ")" ::: "memory")
; #define PG8_BAR __builtin_amdgcn_s_barrier()
; #define PG8_SCHED __builtin_amdgcn_sched_barrier(0)
; template <class Epi, class Sched, bool ALIGN_EPI = false, bool SP2 = false>
; __device__ __forceinline__ void gemm_phase(PG8_LAS unsigned char* lds, const Gemm g, const Sched& S, const Epi& E, int tid_in) {
;     ...
;             PG8_WAIT_V(8); PG8_WAIT_L(0); PG8_BAR; PG8_MMA(1, 0, At, B0); PG8_MMA(1, 1, At, B1); PG8_BAR; PG8_SCHED;
;             PG8_LDB(B0, 1, 0); PG8_LDB(B1, 1, 1); PG8_SCHED; PG8_LDA(At, 1, 0); PG8_STAGE(PG8_SA(0, 1), a2 + hstep, voffA);
;             PG8_WAIT_V(8); PG8_WAIT_L(0); PG8_BAR; PG8_MMA(0, 0, At, B0); PG8_MMA(0, 1, At, B1); PG8_BAR; PG8_SCHED;
	s_setprio 1
	s_waitcnt lgkmcnt(0)
	v_mfma_f32_16x16x32_bf16 v[62:65], v[106:109], v[162:165], 0
	v_mfma_f32_16x16x32_bf16 v[58:61], v[130:133], v[162:165], 0
	v_mfma_f32_16x16x32_bf16 v[46:49], v[106:109], v[170:173], 0
	v_mfma_f32_16x16x32_bf16 v[42:45], v[130:133], v[170:173], 0
	v_mfma_f32_16x16x32_bf16 v[30:33], v[106:109], v[178:181], 0
	v_mfma_f32_16x16x32_bf16 v[26:29], v[130:133], v[178:181], 0
	v_mfma_f32_16x16x32_bf16 v[14:17], v[106:109], v[206:209], 0
	v_mfma_f32_16x16x32_bf16 v[10:13], v[130:133], v[206:209], 0
	v_mfma_f32_16x16x32_bf16 v[62:65], v[110:113], v[166:169], v[62:65]
	v_mfma_f32_16x16x32_bf16 v[58:61], v[134:137], v[166:169], v[58:61]
	v_mfma_f32_16x16x32_bf16 v[46:49], v[110:113], v[174:177], v[46:49]
	v_mfma_f32_16x16x32_bf16 v[42:45], v[134:137], v[174:177], v[42:45]
	v_mfma_f32_16x16x32_bf16 v[30:33], v[110:113], v[182:185], v[30:33]
	v_mfma_f32_16x16x32_bf16 v[26:29], v[134:137], v[182:185], v[26:29]
	v_mfma_f32_16x16x32_bf16 v[14:17], v[110:113], v[212:215], v[14:17]
	v_mfma_f32_16x16x32_bf16 v[10:13], v[134:137], v[212:215], v[10:13]
	s_setprio 0
	s_setprio 1
	v_mfma_f32_16x16x32_bf16 v[54:57], v[146:149], v[162:165], 0
	v_mfma_f32_16x16x32_bf16 v[50:53], v[154:157], v[162:165], 0
	v_mfma_f32_16x16x32_bf16 v[38:41], v[146:149], v[170:173], 0
	v_mfma_f32_16x16x32_bf16 v[34:37], v[154:157], v[170:173], 0
	v_mfma_f32_16x16x32_bf16 v[22:25], v[146:149], v[178:181], 0
	v_mfma_f32_16x16x32_bf16 v[18:21], v[154:157], v[178:181], 0
	v_mfma_f32_16x16x32_bf16 v[6:9], v[146:149], v[206:209], 0
	v_mfma_f32_16x16x32_bf16 v[2:5], v[154:157], v[206:209], 0
	v_mfma_f32_16x16x32_bf16 v[54:57], v[150:153], v[166:169], v[54:57]
	v_mfma_f32_16x16x32_bf16 v[50:53], v[158:161], v[166:169], v[50:53]
	v_mfma_f32_16x16x32_bf16 v[38:41], v[150:153], v[174:177], v[38:41]
	v_mfma_f32_16x16x32_bf16 v[34:37], v[158:161], v[174:177], v[34:37]
	v_mfma_f32_16x16x32_bf16 v[22:25], v[150:153], v[182:185], v[22:25]
	v_mfma_f32_16x16x32_bf16 v[18:21], v[158:161], v[182:185], v[18:21]
	v_mfma_f32_16x16x32_bf16 v[6:9], v[150:153], v[212:215], v[6:9]
	v_mfma_f32_16x16x32_bf16 v[2:5], v[158:161], v[212:215], v[2:5]
	s_setprio 0
	s_barrier
	v_add_u32_e32 v134, s33, v210
	v_add_u32_e32 v158, s74, v210
	ds_read_b128 v[106:109], v134
	ds_read_b128 v[110:113], v134 offset:1024
	ds_read_b128 v[130:133], v134 offset:2048
	ds_read_b128 v[134:137], v134 offset:3072
	ds_read_b128 v[146:149], v158
	ds_read_b128 v[150:153], v158 offset:1024
	ds_read_b128 v[154:157], v158 offset:2048
	ds_read_b128 v[158:161], v158 offset:3072
	s_add_u32 s54, s54, 0x100000
	s_addc_u32 s55, s55, 0
	s_mov_b32 m0, s63
	v_lshl_add_u64 v[224:225], s[54:55], 0, v[200:201]
	ds_read_b128 v[162:165], v211 offset:32768
	ds_read_b128 v[166:169], v211 offset:33792
	ds_read_b128 v[170:173], v211 offset:34816
	ds_read_b128 v[174:177], v211 offset:35840
	ds_read_b128 v[178:181], v211 offset:36864
	ds_read_b128 v[182:185], v211 offset:37888
	ds_read_b128 v[206:209], v211 offset:38912
	ds_read_b128 v[212:215], v211 offset:39936
	global_load_lds_dwordx4 v[224:225], off
	v_lshl_add_u64 v[224:225], s[54:55], 0, v[198:199]
	s_mov_b32 m0, s64
	s_nop 0
	global_load_lds_dwordx4 v[224:225], off
	s_waitcnt vmcnt(8)
	s_waitcnt lgkmcnt(0)
	s_barrier
	s_setprio 1
	s_waitcnt lgkmcnt(0)
	v_mfma_f32_16x16x32_bf16 v[142:145], v[106:109], v[162:165], v[142:145]
	v_mfma_f32_16x16x32_bf16 v[138:141], v[130:133], v[162:165], v[138:141]
	v_mfma_f32_16x16x32_bf16 v[118:121], v[106:109], v[170:173], v[118:121]
	v_mfma_f32_16x16x32_bf16 v[114:117], v[130:133], v[170:173], v[114:117]
	v_mfma_f32_16x16x32_bf16 v[94:97], v[106:109], v[178:181], v[94:97]
	v_mfma_f32_16x16x32_bf16 v[90:93], v[130:133], v[178:181], v[90:93]
	v_mfma_f32_16x16x32_bf16 v[78:81], v[106:109], v[206:209], v[78:81]
	v_mfma_f32_16x16x32_bf16 v[74:77], v[130:133], v[206:209], v[74:77]
	v_mfma_f32_16x16x32_bf16 v[142:145], v[110:113], v[166:169], v[142:145]
	v_mfma_f32_16x16x32_bf16 v[138:141], v[134:137], v[166:169], v[138:141]
	v_mfma_f32_16x16x32_bf16 v[118:121], v[110:113], v[174:177], v[118:121]
	v_mfma_f32_16x16x32_bf16 v[114:117], v[134:137], v[174:177], v[114:117]
	v_mfma_f32_16x16x32_bf16 v[94:97], v[110:113], v[182:185], v[94:97]
	v_mfma_f32_16x16x32_bf16 v[90:93], v[134:137], v[182:185], v[90:93]
	v_mfma_f32_16x16x32_bf16 v[78:81], v[110:113], v[212:215], v[78:81]
	v_mfma_f32_16x16x32_bf16 v[74:77], v[134:137], v[212:215], v[74:77]
	s_setprio 0
	s_setprio 1
	v_mfma_f32_16x16x32_bf16 v[126:129], v[146:149], v[162:165], v[126:129]
	v_mfma_f32_16x16x32_bf16 v[122:125], v[154:157], v[162:165], v[122:125]
	v_mfma_f32_16x16x32_bf16 v[102:105], v[146:149], v[170:173], v[102:105]
	v_mfma_f32_16x16x32_bf16 v[98:101], v[154:157], v[170:173], v[98:101]
	v_mfma_f32_16x16x32_bf16 v[86:89], v[146:149], v[178:181], v[86:89]
	v_mfma_f32_16x16x32_bf16 v[82:85], v[154:157], v[178:181], v[82:85]
	v_mfma_f32_16x16x32_bf16 v[70:73], v[146:149], v[206:209], v[70:73]
	v_mfma_f32_16x16x32_bf16 v[66:69], v[154:157], v[206:209], v[66:69]
	v_mfma_f32_16x16x32_bf16 v[126:129], v[150:153], v[166:169], v[126:129]
	v_mfma_f32_16x16x32_bf16 v[122:125], v[158:161], v[166:169], v[122:125]
	v_mfma_f32_16x16x32_bf16 v[102:105], v[150:153], v[174:177], v[102:105]
	v_mfma_f32_16x16x32_bf16 v[98:101], v[158:161], v[174:177], v[98:101]
	v_mfma_f32_16x16x32_bf16 v[86:89], v[150:153], v[182:185], v[86:89]
	v_mfma_f32_16x16x32_bf16 v[82:85], v[158:161], v[182:185], v[82:85]
	v_mfma_f32_16x16x32_bf16 v[70:73], v[150:153], v[212:215], v[70:73]
	v_mfma_f32_16x16x32_bf16 v[66:69], v[158:161], v[212:215], v[66:69]
	s_setprio 0
	s_barrier
; #define PG8_STAGE(bufoff, gbase, voff) do { _Pragma("unroll") for (int _i = 0; _i < 2; ++_i) \
;         __builtin_amdgcn_global_load_lds((const unsigned*)((const char*)(gbase) + (voff)[_i]), (PG8_LAS unsigned*)(lds + (bufoff) + ldsw + _i * 8192), 16, 0, 0); } while (0)
; #define PG8_LDA(dst, b, h) do { _Pragma("unroll") for (int m = 0; m < 4; ++m) _Pragma("unroll") for (int k = 0; k < 2; ++k) dst[m][k] = *(const PG8_LAS bf16x8*)(lds + PG8_SA(b, h) + aoff + m * 2048 + k * 1024); } while (0)
; #define PG8_MMA(ai, bj, At, Bt) do { __builtin_amdgcn_s_setprio(1); _Pragma("unroll") for (int k = 0; k < 2; ++k) _Pragma("unroll") for (int m = 0; m < 4; ++m) _Pragma("unroll") for (int n = 0; n < 2; ++n) \
;         acc[ai][bj][m][n] = __builtin_amdgcn_mfma_f32_16x16x32_bf16(Bt[n][k], At[m][k], acc[ai][bj][m][n], 0, 0, 0); __builtin_amdgcn_s_setprio(0); } while (0)
; #define PG8_WAIT_V(n) asm volatile("s_waitcnt vmcnt(" #n ")" ::: "memory")
; #define PG8_WAIT_L(n) asm volatile("s_waitcnt lgkmcnt(" #n ")" ::: "memory")
; #define PG8_BAR __builtin_amdgcn_s_barrier()
; #define PG8_SCHED __builtin_amdgcn_sched_barrier(0)
; template <class Epi, class Sched, bool ALIGN_EPI = false, bool SP2 = false>
; __device__ __forceinline__ void gemm_phase(PG8_LAS unsigned char* lds, const Gemm g, const Sched& S, const Epi& E, int tid_in) {
;     ...
;             PG8_LDA(At, 1, 1); PG8_STAGE(PG8_SB(1, 0), b3, voffB); PG8_STAGE(PG8_SB(1, 1), b3 + hstep, voffB); PG8_STAGE(PG8_SA(1, 0), a3, voffA);
;             PG8_WAIT_V(8); PG8_WAIT_L(0); PG8_BAR; PG8_MMA(1, 0, At, B0); PG8_MMA(1, 1, At, B1); PG8_BAR; PG8_SCHED;
	s_add_i32 s54, s33, s60
	v_lshl_add_u64 v[216:217], v[216:217], 0, s[26:27]
	s_mov_b32 m0, s54
	ds_read_b128 v[162:165], v211 offset:49152
	ds_read_b128 v[166:169], v211 offset:50176
	ds_read_b128 v[170:173], v211 offset:51200
	ds_read_b128 v[174:177], v211 offset:52224
	ds_read_b128 v[178:181], v211 offset:53248
	ds_read_b128 v[182:185], v211 offset:54272
	ds_read_b128 v[206:209], v211 offset:55296
	ds_read_b128 v[212:215], v211 offset:56320
	global_load_lds_dwordx4 v[216:217], off
	s_add_i32 m0, s54, 0x2000
	s_add_u32 s52, s52, 0x100080
	v_lshl_add_u64 v[216:217], v[218:219], 0, s[26:27]
	s_addc_u32 s53, s53, 0
	s_add_i32 s54, s74, s60
	global_load_lds_dwordx4 v[216:217], off
	v_lshl_add_u64 v[216:217], s[52:53], 0, v[0:1]
	s_mov_b32 m0, s54
	s_nop 0
	global_load_lds_dwordx4 v[216:217], off
	v_lshl_add_u64 v[216:217], s[52:53], 0, v[196:197]
	s_add_i32 m0, s54, 0x2000
	s_nop 0
	global_load_lds_dwordx4 v[216:217], off
	v_lshl_add_u64 v[216:217], v[220:221], 0, s[26:27]
	s_mov_b32 m0, s75
	s_nop 0
	global_load_lds_dwordx4 v[216:217], off
	v_lshl_add_u64 v[216:217], v[222:223], 0, s[26:27]
	s_mov_b32 m0, s76
	s_nop 0
	global_load_lds_dwordx4 v[216:217], off
	s_waitcnt vmcnt(8)
	s_waitcnt lgkmcnt(0)
	s_barrier
	s_setprio 1
	s_waitcnt lgkmcnt(0)
	v_mfma_f32_16x16x32_bf16 v[62:65], v[106:109], v[162:165], v[62:65]
	v_mfma_f32_16x16x32_bf16 v[58:61], v[130:133], v[162:165], v[58:61]
	v_mfma_f32_16x16x32_bf16 v[46:49], v[106:109], v[170:173], v[46:49]
	v_mfma_f32_16x16x32_bf16 v[42:45], v[130:133], v[170:173], v[42:45]
	v_mfma_f32_16x16x32_bf16 v[30:33], v[106:109], v[178:181], v[30:33]
	v_mfma_f32_16x16x32_bf16 v[26:29], v[130:133], v[178:181], v[26:29]
	v_mfma_f32_16x16x32_bf16 v[14:17], v[106:109], v[206:209], v[14:17]
	v_mfma_f32_16x16x32_bf16 v[10:13], v[130:133], v[206:209], v[10:13]
	v_mfma_f32_16x16x32_bf16 v[62:65], v[110:113], v[166:169], v[62:65]
	v_mfma_f32_16x16x32_bf16 v[58:61], v[134:137], v[166:169], v[58:61]
	v_mfma_f32_16x16x32_bf16 v[46:49], v[110:113], v[174:177], v[46:49]
	v_mfma_f32_16x16x32_bf16 v[42:45], v[134:137], v[174:177], v[42:45]
	v_mfma_f32_16x16x32_bf16 v[30:33], v[110:113], v[182:185], v[30:33]
	v_mfma_f32_16x16x32_bf16 v[26:29], v[134:137], v[182:185], v[26:29]
	v_mfma_f32_16x16x32_bf16 v[14:17], v[110:113], v[212:215], v[14:17]
	v_mfma_f32_16x16x32_bf16 v[10:13], v[134:137], v[212:215], v[10:13]
	s_setprio 0
	s_setprio 1
	v_mfma_f32_16x16x32_bf16 v[54:57], v[146:149], v[162:165], v[54:57]
	v_mfma_f32_16x16x32_bf16 v[50:53], v[154:157], v[162:165], v[50:53]
	v_mfma_f32_16x16x32_bf16 v[38:41], v[146:149], v[170:173], v[38:41]
	v_mfma_f32_16x16x32_bf16 v[34:37], v[154:157], v[170:173], v[34:37]
	v_mfma_f32_16x16x32_bf16 v[22:25], v[146:149], v[178:181], v[22:25]
	v_mfma_f32_16x16x32_bf16 v[18:21], v[154:157], v[178:181], v[18:21]
	v_mfma_f32_16x16x32_bf16 v[6:9], v[146:149], v[206:209], v[6:9]
	v_mfma_f32_16x16x32_bf16 v[2:5], v[154:157], v[206:209], v[2:5]
	v_mfma_f32_16x16x32_bf16 v[54:57], v[150:153], v[166:169], v[54:57]
	v_mfma_f32_16x16x32_bf16 v[50:53], v[158:161], v[166:169], v[50:53]
	v_mfma_f32_16x16x32_bf16 v[38:41], v[150:153], v[174:177], v[38:41]
	v_mfma_f32_16x16x32_bf16 v[34:37], v[158:161], v[174:177], v[34:37]
	v_mfma_f32_16x16x32_bf16 v[22:25], v[150:153], v[182:185], v[22:25]
	v_mfma_f32_16x16x32_bf16 v[18:21], v[158:161], v[182:185], v[18:21]
	v_mfma_f32_16x16x32_bf16 v[6:9], v[150:153], v[212:215], v[6:9]
	v_mfma_f32_16x16x32_bf16 v[2:5], v[158:161], v[212:215], v[2:5]
	s_setprio 0
	s_barrier
	s_add_i32 s83, s83, 2
	s_add_u32 s50, s50, 0x100
	s_addc_u32 s51, s51, 0
	s_add_u32 s81, s81, 0x100
	s_addc_u32 s82, s82, 0
	s_cmp_gt_u32 s83, 61
